# prep phase: software-pipelined adaLN GEMV and filter GEMM loops; hyena epilogue load hoist
# speedup vs baseline: 1.0130x; 1.0130x over previous
; DI void filter_item(const Params& p, char* wsb, int it, char* lds) {
;     ...
; #pragma unroll 1
;   for (int g = 0; g < 8; ++g) {
;     float acc[4][8];
; #pragma unroll
;     for (int a = 0; a < 4; ++a)
; #pragma unroll
;       for (int b = 0; b < 8; ++b) acc[a][b] = 0.f;
; #pragma unroll 2
;     for (int f = 0; f < 64; ++f) {
;       float4 w0 = *(const float4*)(wout + (size_t)f * 2048), w1 = *(const float4*)(wout + (size_t)f * 2048 + 4);
;       float wv[8] = {w0.x, w0.y, w0.z, w0.w, w1.x, w1.y, w1.z, w1.w};
; #pragma unroll
;       for (int lg = 0; lg < 4; ++lg) {
;         float av = a0[(4 * g + lg) * 64 + f];
; #pragma unroll
;         for (int cc = 0; cc < 8; ++cc) acc[lg][cc] += av * wv[cc];
;       }
;     }
.LBB0_170:
	v_mov_b32_e32 v34, 0
	s_mov_b64 s[54:55], 0
	s_mov_b32 s4, s8
	v_mov_b32_e32 v35, v34
	v_mov_b32_e32 v36, v34
	v_mov_b32_e32 v37, v34
	v_mov_b32_e32 v30, v34
	v_mov_b32_e32 v31, v34
	v_mov_b32_e32 v32, v34
	v_mov_b32_e32 v33, v34
	v_mov_b32_e32 v26, v34
	v_mov_b32_e32 v27, v34
	v_mov_b32_e32 v28, v34
	v_mov_b32_e32 v29, v34
	v_mov_b32_e32 v22, v34
	v_mov_b32_e32 v23, v34
	v_mov_b32_e32 v24, v34
	v_mov_b32_e32 v25, v34
	v_mov_b32_e32 v18, v34
	v_mov_b32_e32 v19, v34
	v_mov_b32_e32 v20, v34
	v_mov_b32_e32 v21, v34
	v_mov_b32_e32 v14, v34
	v_mov_b32_e32 v15, v34
	v_mov_b32_e32 v16, v34
	v_mov_b32_e32 v17, v34
	v_mov_b32_e32 v10, v34
	v_mov_b32_e32 v11, v34
	v_mov_b32_e32 v12, v34
	v_mov_b32_e32 v13, v34
	v_mov_b32_e32 v6, v34
	v_mov_b32_e32 v7, v34
	v_mov_b32_e32 v8, v34
	v_mov_b32_e32 v9, v34
	v_lshl_add_u64 v[76:77], v[2:3], 0, s[54:55]
	global_load_dwordx4 v[68:71], v[76:77], off
	global_load_dwordx4 v[72:75], v[76:77], off offset:16
	v_lshl_add_u64 v[80:81], v[76:77], 0, s[34:35]
	v_add_co_u32_e32 v76, vcc, s76, v76
	s_nop 0
	v_addc_co_u32_e32 v77, vcc, 0, v77, vcc
	global_load_dwordx4 v[76:79], v[76:77], off
	s_nop 0
	global_load_dwordx4 v[80:83], v[80:81], off offset:16
	s_add_u32 s54, s54, 0x4000
	s_addc_u32 s55, s55, 0
	s_mov_b32 s47, 16
.LBB0_171:
	v_lshl_add_u64 v[204:205], v[2:3], 0, s[54:55]
	global_load_dwordx4 v[196:199], v[204:205], off
	global_load_dwordx4 v[200:203], v[204:205], off offset:16
	v_lshl_add_u64 v[208:209], v[204:205], 0, s[34:35]
	v_add_co_u32_e32 v204, vcc, s76, v204
	s_nop 0
	v_addc_co_u32_e32 v205, vcc, 0, v205, vcc
	global_load_dwordx4 v[204:207], v[204:205], off
	s_nop 0
	global_load_dwordx4 v[208:211], v[208:209], off offset:16
	s_add_u32 s54, s54, 0x4000
	s_addc_u32 s55, s55, 0
	v_mov_b32_e32 v88, s4
	ds_read2_b64 v[84:87], v88 offset1:32
	ds_read2_b64 v[88:91], v88 offset0:64 offset1:96
	s_add_i32 s4, s4, 8
	s_waitcnt lgkmcnt(1)
	v_mov_b32_e32 v92, v84
	v_mov_b32_e32 v93, v86
	s_waitcnt lgkmcnt(0)
	v_mov_b32_e32 v94, v88
	v_mov_b32_e32 v95, v90
	v_mov_b32_e32 v86, v85
	v_mov_b32_e32 v90, v89
	s_waitcnt vmcnt(7)
	v_mov_b32_e32 v84, v71
	s_waitcnt vmcnt(6)
	v_mov_b32_e32 v88, v75
	v_pk_fma_f32 v[36:37], v[68:69], v[92:93], v[36:37] op_sel_hi:[0,1,1]
	v_pk_fma_f32 v[32:33], v[68:69], v[92:93], v[32:33] op_sel:[1,0,0]
	v_pk_fma_f32 v[28:29], v[70:71], v[92:93], v[28:29] op_sel_hi:[0,1,1]
	v_pk_fma_f32 v[20:21], v[72:73], v[92:93], v[20:21] op_sel_hi:[0,1,1]
	v_pk_fma_f32 v[16:17], v[72:73], v[92:93], v[16:17] op_sel:[1,0,0]
	v_pk_fma_f32 v[12:13], v[74:75], v[92:93], v[12:13] op_sel_hi:[0,1,1]
	v_pk_fma_f32 v[34:35], v[68:69], v[94:95], v[34:35] op_sel_hi:[0,1,1]
	v_pk_fma_f32 v[30:31], v[68:69], v[94:95], v[30:31] op_sel:[1,0,0]
	v_pk_fma_f32 v[26:27], v[70:71], v[94:95], v[26:27] op_sel_hi:[0,1,1]
	v_pk_fma_f32 v[18:19], v[72:73], v[94:95], v[18:19] op_sel_hi:[0,1,1]
	v_pk_fma_f32 v[14:15], v[72:73], v[94:95], v[14:15] op_sel:[1,0,0]
	v_pk_fma_f32 v[10:11], v[74:75], v[94:95], v[10:11] op_sel_hi:[0,1,1]
	v_pk_fma_f32 v[24:25], v[84:85], v[92:93], v[24:25] op_sel_hi:[0,1,1]
	v_pk_fma_f32 v[8:9], v[88:89], v[92:93], v[8:9] op_sel_hi:[0,1,1]
	v_pk_fma_f32 v[22:23], v[84:85], v[94:95], v[22:23] op_sel_hi:[0,1,1]
	v_pk_fma_f32 v[6:7], v[88:89], v[94:95], v[6:7] op_sel_hi:[0,1,1]
	s_waitcnt vmcnt(5)
	v_mov_b32_e32 v68, v79
	s_waitcnt vmcnt(4)
	v_mov_b32_e32 v70, v83
	v_pk_fma_f32 v[36:37], v[76:77], v[86:87], v[36:37] op_sel_hi:[0,1,1]
	v_pk_fma_f32 v[32:33], v[76:77], v[86:87], v[32:33] op_sel:[1,0,0]
	v_pk_fma_f32 v[28:29], v[78:79], v[86:87], v[28:29] op_sel_hi:[0,1,1]
	v_pk_fma_f32 v[20:21], v[80:81], v[86:87], v[20:21] op_sel_hi:[0,1,1]
	v_pk_fma_f32 v[16:17], v[80:81], v[86:87], v[16:17] op_sel:[1,0,0]
	v_pk_fma_f32 v[12:13], v[82:83], v[86:87], v[12:13] op_sel_hi:[0,1,1]
	v_pk_fma_f32 v[34:35], v[76:77], v[90:91], v[34:35] op_sel_hi:[0,1,1]
	v_pk_fma_f32 v[30:31], v[76:77], v[90:91], v[30:31] op_sel:[1,0,0]
	v_pk_fma_f32 v[26:27], v[78:79], v[90:91], v[26:27] op_sel_hi:[0,1,1]
	v_pk_fma_f32 v[18:19], v[80:81], v[90:91], v[18:19] op_sel_hi:[0,1,1]
	v_pk_fma_f32 v[14:15], v[80:81], v[90:91], v[14:15] op_sel:[1,0,0]
	v_pk_fma_f32 v[10:11], v[82:83], v[90:91], v[10:11] op_sel_hi:[0,1,1]
	v_pk_fma_f32 v[24:25], v[68:69], v[86:87], v[24:25] op_sel_hi:[0,1,1]
	v_pk_fma_f32 v[8:9], v[70:71], v[86:87], v[8:9] op_sel_hi:[0,1,1]
	v_pk_fma_f32 v[22:23], v[68:69], v[90:91], v[22:23] op_sel_hi:[0,1,1]
	v_pk_fma_f32 v[6:7], v[70:71], v[90:91], v[6:7] op_sel_hi:[0,1,1]
	s_cmp_eq_u32 s47, 1
	s_cbranch_scc1 .Lflt_last
; DI void filter_item(const Params& p, char* wsb, int it, char* lds) {
;     ...
; #pragma unroll 1
;   for (int g = 0; g < 8; ++g) {
;     float acc[4][8];
; #pragma unroll
;     for (int a = 0; a < 4; ++a)
; #pragma unroll
;       for (int b = 0; b < 8; ++b) acc[a][b] = 0.f;
; #pragma unroll 2
;     for (int f = 0; f < 64; ++f) {
;       float4 w0 = *(const float4*)(wout + (size_t)f * 2048), w1 = *(const float4*)(wout + (size_t)f * 2048 + 4);
;       float wv[8] = {w0.x, w0.y, w0.z, w0.w, w1.x, w1.y, w1.z, w1.w};
; #pragma unroll
;       for (int lg = 0; lg < 4; ++lg) {
;         float av = a0[(4 * g + lg) * 64 + f];
; #pragma unroll
;         for (int cc = 0; cc < 8; ++cc) acc[lg][cc] += av * wv[cc];
;       }
;     }
	v_lshl_add_u64 v[76:77], v[2:3], 0, s[54:55]
	global_load_dwordx4 v[68:71], v[76:77], off
	global_load_dwordx4 v[72:75], v[76:77], off offset:16
	v_lshl_add_u64 v[80:81], v[76:77], 0, s[34:35]
	v_add_co_u32_e32 v76, vcc, s76, v76
	s_nop 0
	v_addc_co_u32_e32 v77, vcc, 0, v77, vcc
	global_load_dwordx4 v[76:79], v[76:77], off
	s_nop 0
	global_load_dwordx4 v[80:83], v[80:81], off offset:16
	s_add_u32 s54, s54, 0x4000
	s_addc_u32 s55, s55, 0
	v_mov_b32_e32 v88, s4
	ds_read2_b64 v[84:87], v88 offset1:32
	ds_read2_b64 v[88:91], v88 offset0:64 offset1:96
	s_add_i32 s4, s4, 8
	s_waitcnt lgkmcnt(1)
	v_mov_b32_e32 v92, v84
	v_mov_b32_e32 v93, v86
	s_waitcnt lgkmcnt(0)
	v_mov_b32_e32 v94, v88
	v_mov_b32_e32 v95, v90
	v_mov_b32_e32 v86, v85
	v_mov_b32_e32 v90, v89
	s_waitcnt vmcnt(7)
	v_mov_b32_e32 v84, v199
	s_waitcnt vmcnt(6)
	v_mov_b32_e32 v88, v203
	v_pk_fma_f32 v[36:37], v[196:197], v[92:93], v[36:37] op_sel_hi:[0,1,1]
	v_pk_fma_f32 v[32:33], v[196:197], v[92:93], v[32:33] op_sel:[1,0,0]
	v_pk_fma_f32 v[28:29], v[198:199], v[92:93], v[28:29] op_sel_hi:[0,1,1]
	v_pk_fma_f32 v[20:21], v[200:201], v[92:93], v[20:21] op_sel_hi:[0,1,1]
	v_pk_fma_f32 v[16:17], v[200:201], v[92:93], v[16:17] op_sel:[1,0,0]
	v_pk_fma_f32 v[12:13], v[202:203], v[92:93], v[12:13] op_sel_hi:[0,1,1]
	v_pk_fma_f32 v[34:35], v[196:197], v[94:95], v[34:35] op_sel_hi:[0,1,1]
	v_pk_fma_f32 v[30:31], v[196:197], v[94:95], v[30:31] op_sel:[1,0,0]
	v_pk_fma_f32 v[26:27], v[198:199], v[94:95], v[26:27] op_sel_hi:[0,1,1]
	v_pk_fma_f32 v[18:19], v[200:201], v[94:95], v[18:19] op_sel_hi:[0,1,1]
	v_pk_fma_f32 v[14:15], v[200:201], v[94:95], v[14:15] op_sel:[1,0,0]
	v_pk_fma_f32 v[10:11], v[202:203], v[94:95], v[10:11] op_sel_hi:[0,1,1]
	v_pk_fma_f32 v[24:25], v[84:85], v[92:93], v[24:25] op_sel_hi:[0,1,1]
	v_pk_fma_f32 v[8:9], v[88:89], v[92:93], v[8:9] op_sel_hi:[0,1,1]
	v_pk_fma_f32 v[22:23], v[84:85], v[94:95], v[22:23] op_sel_hi:[0,1,1]
	v_pk_fma_f32 v[6:7], v[88:89], v[94:95], v[6:7] op_sel_hi:[0,1,1]
	s_waitcnt vmcnt(5)
	v_mov_b32_e32 v196, v207
	s_waitcnt vmcnt(4)
	v_mov_b32_e32 v198, v211
	v_pk_fma_f32 v[36:37], v[204:205], v[86:87], v[36:37] op_sel_hi:[0,1,1]
	v_pk_fma_f32 v[32:33], v[204:205], v[86:87], v[32:33] op_sel:[1,0,0]
	v_pk_fma_f32 v[28:29], v[206:207], v[86:87], v[28:29] op_sel_hi:[0,1,1]
	v_pk_fma_f32 v[20:21], v[208:209], v[86:87], v[20:21] op_sel_hi:[0,1,1]
	v_pk_fma_f32 v[16:17], v[208:209], v[86:87], v[16:17] op_sel:[1,0,0]
	v_pk_fma_f32 v[12:13], v[210:211], v[86:87], v[12:13] op_sel_hi:[0,1,1]
	v_pk_fma_f32 v[34:35], v[204:205], v[90:91], v[34:35] op_sel_hi:[0,1,1]
	v_pk_fma_f32 v[30:31], v[204:205], v[90:91], v[30:31] op_sel:[1,0,0]
	v_pk_fma_f32 v[26:27], v[206:207], v[90:91], v[26:27] op_sel_hi:[0,1,1]
	v_pk_fma_f32 v[18:19], v[208:209], v[90:91], v[18:19] op_sel_hi:[0,1,1]
	v_pk_fma_f32 v[14:15], v[208:209], v[90:91], v[14:15] op_sel:[1,0,0]
	v_pk_fma_f32 v[10:11], v[210:211], v[90:91], v[10:11] op_sel_hi:[0,1,1]
	v_pk_fma_f32 v[24:25], v[196:197], v[86:87], v[24:25] op_sel_hi:[0,1,1]
	v_pk_fma_f32 v[8:9], v[198:199], v[86:87], v[8:9] op_sel_hi:[0,1,1]
	v_pk_fma_f32 v[22:23], v[196:197], v[90:91], v[22:23] op_sel_hi:[0,1,1]
	v_pk_fma_f32 v[6:7], v[198:199], v[90:91], v[6:7] op_sel_hi:[0,1,1]
	s_sub_u32 s47, s47, 1
	s_branch .LBB0_171
.Lflt_last:
	v_mov_b32_e32 v88, s4
	ds_read2_b64 v[84:87], v88 offset1:32
	ds_read2_b64 v[88:91], v88 offset0:64 offset1:96
	s_add_i32 s4, s4, 8
	s_waitcnt lgkmcnt(1)
	v_mov_b32_e32 v92, v84
	v_mov_b32_e32 v93, v86
	s_waitcnt lgkmcnt(0)
	v_mov_b32_e32 v94, v88
	v_mov_b32_e32 v95, v90
	v_mov_b32_e32 v86, v85
	v_mov_b32_e32 v90, v89
	s_waitcnt vmcnt(3)
	v_mov_b32_e32 v84, v199
	s_waitcnt vmcnt(2)
	v_mov_b32_e32 v88, v203
	v_pk_fma_f32 v[36:37], v[196:197], v[92:93], v[36:37] op_sel_hi:[0,1,1]
	v_pk_fma_f32 v[32:33], v[196:197], v[92:93], v[32:33] op_sel:[1,0,0]
	v_pk_fma_f32 v[28:29], v[198:199], v[92:93], v[28:29] op_sel_hi:[0,1,1]
	v_pk_fma_f32 v[20:21], v[200:201], v[92:93], v[20:21] op_sel_hi:[0,1,1]
	v_pk_fma_f32 v[16:17], v[200:201], v[92:93], v[16:17] op_sel:[1,0,0]
	v_pk_fma_f32 v[12:13], v[202:203], v[92:93], v[12:13] op_sel_hi:[0,1,1]
	v_pk_fma_f32 v[34:35], v[196:197], v[94:95], v[34:35] op_sel_hi:[0,1,1]
	v_pk_fma_f32 v[30:31], v[196:197], v[94:95], v[30:31] op_sel:[1,0,0]
	v_pk_fma_f32 v[26:27], v[198:199], v[94:95], v[26:27] op_sel_hi:[0,1,1]
	v_pk_fma_f32 v[18:19], v[200:201], v[94:95], v[18:19] op_sel_hi:[0,1,1]
	v_pk_fma_f32 v[14:15], v[200:201], v[94:95], v[14:15] op_sel:[1,0,0]
	v_pk_fma_f32 v[10:11], v[202:203], v[94:95], v[10:11] op_sel_hi:[0,1,1]
	v_pk_fma_f32 v[24:25], v[84:85], v[92:93], v[24:25] op_sel_hi:[0,1,1]
	v_pk_fma_f32 v[8:9], v[88:89], v[92:93], v[8:9] op_sel_hi:[0,1,1]
	v_pk_fma_f32 v[22:23], v[84:85], v[94:95], v[22:23] op_sel_hi:[0,1,1]
	v_pk_fma_f32 v[6:7], v[88:89], v[94:95], v[6:7] op_sel_hi:[0,1,1]
	s_waitcnt vmcnt(1)
	v_mov_b32_e32 v196, v207
	s_waitcnt vmcnt(0)
; DI void filter_item(const Params& p, char* wsb, int it, char* lds) {
;     ...
; #pragma unroll
;     for (int cc = 0; cc < 8; ++cc) {
;       float delta = fabsf(mind + (maxd - mind) * ((float)(c0 + cc) / 511.f));
;       float v[4];
; #pragma unroll
;       for (int lg = 0; lg < 4; ++lg) {
;         float t = (float)(l0 + 4 * g + lg) / (float)(L - 1);
;         v[lg] = acc[lg][cc] * __expf(-t * delta);
;       }
;       *(uint2*)(dstb + (size_t)cc * L + l0 + 4 * g) = make_uint2(pack2(v[0], v[1]), pack2(v[2], v[3]));
;     }
	v_mov_b32_e32 v198, v211
	v_pk_fma_f32 v[36:37], v[204:205], v[86:87], v[36:37] op_sel_hi:[0,1,1]
	v_pk_fma_f32 v[32:33], v[204:205], v[86:87], v[32:33] op_sel:[1,0,0]
	v_pk_fma_f32 v[28:29], v[206:207], v[86:87], v[28:29] op_sel_hi:[0,1,1]
	v_pk_fma_f32 v[20:21], v[208:209], v[86:87], v[20:21] op_sel_hi:[0,1,1]
	v_pk_fma_f32 v[16:17], v[208:209], v[86:87], v[16:17] op_sel:[1,0,0]
	v_pk_fma_f32 v[12:13], v[210:211], v[86:87], v[12:13] op_sel_hi:[0,1,1]
	v_pk_fma_f32 v[34:35], v[204:205], v[90:91], v[34:35] op_sel_hi:[0,1,1]
	v_pk_fma_f32 v[30:31], v[204:205], v[90:91], v[30:31] op_sel:[1,0,0]
	v_pk_fma_f32 v[26:27], v[206:207], v[90:91], v[26:27] op_sel_hi:[0,1,1]
	v_pk_fma_f32 v[18:19], v[208:209], v[90:91], v[18:19] op_sel_hi:[0,1,1]
	v_pk_fma_f32 v[14:15], v[208:209], v[90:91], v[14:15] op_sel:[1,0,0]
	v_pk_fma_f32 v[10:11], v[210:211], v[90:91], v[10:11] op_sel_hi:[0,1,1]
	v_pk_fma_f32 v[24:25], v[196:197], v[86:87], v[24:25] op_sel_hi:[0,1,1]
	v_pk_fma_f32 v[8:9], v[198:199], v[86:87], v[8:9] op_sel_hi:[0,1,1]
	v_pk_fma_f32 v[22:23], v[196:197], v[90:91], v[22:23] op_sel_hi:[0,1,1]
	v_pk_fma_f32 v[6:7], v[198:199], v[90:91], v[6:7] op_sel_hi:[0,1,1]
	s_lshl_b32 s4, s9, 2
	s_add_i32 s11, s4, s40
	v_cvt_f32_i32_e32 v68, s11
	s_or_b32 s13, s11, 1
	v_cvt_f32_i32_e32 v71, s13
	s_or_b32 s13, s11, 2
	v_div_scale_f32 v69, s[54:55], v46, v46, -v68
	v_rcp_f32_e32 v70, v69
	v_div_scale_f32 v72, vcc, -v68, v46, -v68
	s_or_b32 s11, s11, 3
	v_fma_f32 v73, -v69, v70, 1.0
	v_fmac_f32_e32 v70, v73, v70
	v_mul_f32_e32 v73, v72, v70
	v_fma_f32 v74, -v69, v73, v72
	v_fmac_f32_e32 v73, v74, v70
	v_fma_f32 v69, -v69, v73, v72
	v_div_fmas_f32 v69, v69, v70, v73
	v_div_fixup_f32 v74, v69, v46, -v68
	v_div_scale_f32 v69, s[54:55], v46, v46, -v71
	v_rcp_f32_e32 v70, v69
	v_mul_f32_e64 v68, |v48|, v74
	v_mul_f32_e32 v68, 0x3fb8aa3b, v68
	v_exp_f32_e32 v68, v68
	v_fma_f32 v72, -v69, v70, 1.0
	v_fmac_f32_e32 v70, v72, v70
	v_div_scale_f32 v72, vcc, -v71, v46, -v71
	v_mul_f32_e32 v73, v72, v70
	v_fma_f32 v75, -v69, v73, v72
	v_fmac_f32_e32 v73, v75, v70
	v_fma_f32 v69, -v69, v73, v72
	v_cvt_f32_i32_e32 v72, s13
	v_div_fmas_f32 v69, v69, v70, v73
	v_div_fixup_f32 v75, v69, v46, -v71
	v_mul_f32_e64 v69, |v48|, v75
	v_div_scale_f32 v70, s[54:55], v46, v46, -v72
	v_rcp_f32_e32 v71, v70
	v_mul_f32_e32 v69, 0x3fb8aa3b, v69
	v_exp_f32_e32 v69, v69
	s_lshl_b32 s4, s9, 3
	v_fma_f32 v73, -v70, v71, 1.0
	v_fmac_f32_e32 v71, v73, v71
	v_div_scale_f32 v73, vcc, -v72, v46, -v72
	v_mul_f32_e32 v76, v73, v71
	v_fma_f32 v77, -v70, v76, v73
	v_fmac_f32_e32 v76, v77, v71
	v_fma_f32 v70, -v70, v76, v73
	v_cvt_f32_i32_e32 v73, s11
	v_div_fmas_f32 v70, v70, v71, v76
	v_div_fixup_f32 v76, v70, v46, -v72
	v_mul_f32_e64 v70, |v48|, v76
	v_div_scale_f32 v71, s[54:55], v46, v46, -v73
	v_rcp_f32_e32 v72, v71
	v_mul_f32_e32 v70, 0x3fb8aa3b, v70
	v_exp_f32_e32 v70, v70
	v_pk_mul_f32 v[36:37], v[68:69], v[36:37]
	v_fma_f32 v77, -v71, v72, 1.0
	v_fmac_f32_e32 v72, v77, v72
	v_div_scale_f32 v77, vcc, -v73, v46, -v73
	v_mul_f32_e32 v78, v77, v72
	v_fma_f32 v79, -v71, v78, v77
	v_fmac_f32_e32 v78, v79, v72
	v_fma_f32 v71, -v71, v78, v77
	v_div_fmas_f32 v71, v71, v72, v78
	v_div_fixup_f32 v77, v71, v46, -v73
	v_mul_f32_e64 v71, |v48|, v77
	v_mul_f32_e32 v71, 0x3fb8aa3b, v71
	v_exp_f32_e32 v71, v71
	v_cvt_pk_bf16_f32 v36, v36, v37
	v_mul_f32_e64 v68, |v49|, v76
	v_mul_f32_e64 v69, |v49|, v77
	v_pk_mul_f32 v[34:35], v[70:71], v[34:35]
	v_mul_f32_e32 v68, 0x3fb8aa3b, v68
	v_cvt_pk_bf16_f32 v37, v34, v35
	v_mul_f32_e64 v34, |v49|, v74
	v_mul_f32_e64 v35, |v49|, v75
	v_mul_f32_e32 v34, 0x3fb8aa3b, v34
	v_mul_f32_e32 v35, 0x3fb8aa3b, v35
	v_mul_f32_e32 v69, 0x3fb8aa3b, v69
	v_exp_f32_e32 v34, v34
	v_exp_f32_e32 v35, v35
	v_exp_f32_e32 v68, v68
	v_exp_f32_e32 v69, v69
	v_lshl_add_u64 v[72:73], v[4:5], 0, s[4:5]
	v_pk_mul_f32 v[32:33], v[34:35], v[32:33]
	s_mov_b32 s11, s5
	v_pk_mul_f32 v[30:31], v[68:69], v[30:31]
	v_cvt_pk_bf16_f32 v32, v32, v33
	v_cvt_pk_bf16_f32 v33, v30, v31
	v_lshl_add_u64 v[30:31], v[72:73], 0, s[10:11]
; DI void filter_item(const Params& p, char* wsb, int it, char* lds) {
;     ...
; #pragma unroll
;     for (int cc = 0; cc < 8; ++cc) {
;       float delta = fabsf(mind + (maxd - mind) * ((float)(c0 + cc) / 511.f));
;       float v[4];
; #pragma unroll
;       for (int lg = 0; lg < 4; ++lg) {
;         float t = (float)(l0 + 4 * g + lg) / (float)(L - 1);
;         v[lg] = acc[lg][cc] * __expf(-t * delta);
;       }
;       *(uint2*)(dstb + (size_t)cc * L + l0 + 4 * g) = make_uint2(pack2(v[0], v[1]), pack2(v[2], v[3]));
;     }
;   }
;   __syncthreads();
	global_store_dwordx2 v[72:73], v[36:37], off
	v_mul_f32_e64 v34, |v50|, v74
	v_mul_f32_e64 v35, |v50|, v75
	v_mul_f32_e64 v36, |v50|, v76
	v_mul_f32_e64 v37, |v50|, v77
	global_store_dwordx2 v[30:31], v[32:33], off
	v_mul_f32_e64 v30, |v51|, v74
	v_mul_f32_e64 v31, |v51|, v75
	v_mul_f32_e64 v32, |v51|, v76
	v_mul_f32_e64 v33, |v51|, v77
	v_mul_f32_e32 v34, 0x3fb8aa3b, v34
	v_mul_f32_e32 v35, 0x3fb8aa3b, v35
	v_mul_f32_e32 v36, 0x3fb8aa3b, v36
	v_mul_f32_e32 v37, 0x3fb8aa3b, v37
	v_mul_f32_e32 v30, 0x3fb8aa3b, v30
	v_mul_f32_e32 v31, 0x3fb8aa3b, v31
	v_mul_f32_e32 v32, 0x3fb8aa3b, v32
	v_mul_f32_e32 v33, 0x3fb8aa3b, v33
	v_exp_f32_e32 v34, v34
	v_exp_f32_e32 v35, v35
	v_exp_f32_e32 v36, v36
	v_exp_f32_e32 v37, v37
	v_exp_f32_e32 v30, v30
	v_exp_f32_e32 v31, v31
	v_exp_f32_e32 v32, v32
	v_exp_f32_e32 v33, v33
	v_pk_mul_f32 v[28:29], v[34:35], v[28:29]
	v_pk_mul_f32 v[26:27], v[36:37], v[26:27]
	s_mov_b32 s13, s5
	v_pk_mul_f32 v[24:25], v[30:31], v[24:25]
	v_pk_mul_f32 v[22:23], v[32:33], v[22:23]
	s_mov_b32 s15, s5
	v_cvt_pk_bf16_f32 v28, v28, v29
	v_cvt_pk_bf16_f32 v29, v26, v27
	v_lshl_add_u64 v[26:27], v[72:73], 0, s[12:13]
	v_cvt_pk_bf16_f32 v24, v24, v25
	v_cvt_pk_bf16_f32 v25, v22, v23
	v_lshl_add_u64 v[22:23], v[72:73], 0, s[14:15]
	global_store_dwordx2 v[26:27], v[28:29], off
	v_mul_f32_e64 v26, |v64|, v74
	v_mul_f32_e64 v27, |v64|, v75
	v_mul_f32_e64 v28, |v64|, v76
	v_mul_f32_e64 v29, |v64|, v77
	global_store_dwordx2 v[22:23], v[24:25], off
	v_mul_f32_e64 v22, |v65|, v74
	v_mul_f32_e64 v23, |v65|, v75
	v_mul_f32_e64 v24, |v65|, v76
	v_mul_f32_e64 v25, |v65|, v77
	v_mul_f32_e32 v26, 0x3fb8aa3b, v26
	v_mul_f32_e32 v27, 0x3fb8aa3b, v27
	v_mul_f32_e32 v28, 0x3fb8aa3b, v28
	v_mul_f32_e32 v29, 0x3fb8aa3b, v29
	v_mul_f32_e32 v22, 0x3fb8aa3b, v22
	v_mul_f32_e32 v23, 0x3fb8aa3b, v23
	v_mul_f32_e32 v24, 0x3fb8aa3b, v24
	v_mul_f32_e32 v25, 0x3fb8aa3b, v25
	v_exp_f32_e32 v26, v26
	v_exp_f32_e32 v27, v27
	v_exp_f32_e32 v28, v28
	v_exp_f32_e32 v29, v29
	v_exp_f32_e32 v22, v22
	v_exp_f32_e32 v23, v23
	v_exp_f32_e32 v24, v24
	v_exp_f32_e32 v25, v25
	v_pk_mul_f32 v[20:21], v[26:27], v[20:21]
	v_pk_mul_f32 v[18:19], v[28:29], v[18:19]
	s_mov_b32 s47, s5
	v_pk_mul_f32 v[16:17], v[22:23], v[16:17]
	v_pk_mul_f32 v[14:15], v[24:25], v[14:15]
	s_mov_b32 s49, s5
	v_cvt_pk_bf16_f32 v20, v20, v21
	v_cvt_pk_bf16_f32 v21, v18, v19
	v_lshl_add_u64 v[18:19], v[72:73], 0, s[46:47]
	v_cvt_pk_bf16_f32 v16, v16, v17
	v_cvt_pk_bf16_f32 v17, v14, v15
	v_lshl_add_u64 v[14:15], v[72:73], 0, s[48:49]
	global_store_dwordx2 v[18:19], v[20:21], off
	v_mul_f32_e64 v18, |v66|, v74
	v_mul_f32_e64 v19, |v66|, v75
	v_mul_f32_e64 v20, |v66|, v76
	v_mul_f32_e64 v21, |v66|, v77
	global_store_dwordx2 v[14:15], v[16:17], off
	v_mul_f32_e64 v14, |v67|, v74
	v_mul_f32_e64 v15, |v67|, v75
	v_mul_f32_e64 v16, |v67|, v76
	v_mul_f32_e64 v17, |v67|, v77
	v_mul_f32_e32 v18, 0x3fb8aa3b, v18
	v_mul_f32_e32 v19, 0x3fb8aa3b, v19
	v_mul_f32_e32 v20, 0x3fb8aa3b, v20
	v_mul_f32_e32 v21, 0x3fb8aa3b, v21
	v_mul_f32_e32 v14, 0x3fb8aa3b, v14
	v_mul_f32_e32 v15, 0x3fb8aa3b, v15
	v_mul_f32_e32 v16, 0x3fb8aa3b, v16
	v_mul_f32_e32 v17, 0x3fb8aa3b, v17
	v_exp_f32_e32 v18, v18
	v_exp_f32_e32 v19, v19
	v_exp_f32_e32 v20, v20
	v_exp_f32_e32 v21, v21
	v_exp_f32_e32 v14, v14
	v_exp_f32_e32 v15, v15
	v_exp_f32_e32 v16, v16
	v_exp_f32_e32 v17, v17
	v_pk_mul_f32 v[12:13], v[18:19], v[12:13]
	v_pk_mul_f32 v[10:11], v[20:21], v[10:11]
	s_mov_b32 s51, s5
	v_pk_mul_f32 v[8:9], v[14:15], v[8:9]
	v_pk_mul_f32 v[6:7], v[16:17], v[6:7]
	s_mov_b32 s53, s5
	s_add_i32 s9, s9, 1
	s_addk_i32 s8, 0x400
	v_cvt_pk_bf16_f32 v12, v12, v13
	v_cvt_pk_bf16_f32 v13, v10, v11
	v_lshl_add_u64 v[10:11], v[72:73], 0, s[50:51]
	v_cvt_pk_bf16_f32 v8, v8, v9
	v_cvt_pk_bf16_f32 v9, v6, v7
	v_lshl_add_u64 v[6:7], v[72:73], 0, s[52:53]
	s_cmp_eq_u32 s9, 8
	global_store_dwordx2 v[10:11], v[12:13], off
	global_store_dwordx2 v[6:7], v[8:9], off
	s_cbranch_scc0 .LBB0_170
	s_mov_b64 s[40:41], -1
	s_barrier
	s_branch .LBB0_203

; #define NT_LD4(ptr) __builtin_nontemporal_load((const f32x4v*)(ptr))
; DI void mods_partial(const Params& p, char* wsb, int it, char* lds) {
;     ...
;   const float* w = p.w_ada + (size_t)layer * 1024 * 9216 + (size_t)(kc * 128) * 9216 + cgp * 1024 + tid * 4;
;   float acc[9][4];
; #pragma unroll
;   for (int r = 0; r < 9; ++r) { acc[r][0] = acc[r][1] = acc[r][2] = acc[r][3] = 0.f; }
; #pragma unroll 4
;   for (int k = 0; k < 128; ++k) {
;     const f32x4v wq = NT_LD4(w + (size_t)k * 9216);
;     const float4 wv = make_float4(wq[0], wq[1], wq[2], wq[3]);
; #pragma unroll
;     for (int r = 0; r < 9; ++r) {
;       float sv = s[r * 128 + k];
;       acc[r][0] += sv * wv.x; acc[r][1] += sv * wv.y; acc[r][2] += sv * wv.z; acc[r][3] += sv * wv.w;
;     }
;   }
.LBB0_210:
	s_or_b64 exec, exec, s[8:9]
	s_lshl_b32 s8, s13, 7
	s_and_b32 s8, s8, 0xfffffc00
	s_and_b32 s13, s96, 7
	s_mul_i32 s11, s4, 0x2400000
	s_ashr_i32 s9, s8, 31
	s_mul_i32 s13, s13, 0x480000
	s_mul_hi_i32 s10, s4, 0x2400000
	s_add_u32 s13, s11, s13
	s_addc_u32 s14, s10, 0
	s_lshl_b64 s[10:11], s[8:9], 2
	s_add_u32 s10, s13, s10
	s_addc_u32 s11, s14, s11
	s_add_u32 s10, s2, s10
	v_ashrrev_i32_e32 v49, 31, v48
	s_addc_u32 s11, s3, s11
	v_mov_b32_e32 v2, 0
	v_lshl_add_u64 v[50:51], v[48:49], 2, s[10:11]
	s_mov_b64 s[10:11], 0
	s_mov_b32 s13, 0
	v_mov_b32_e32 v3, v2
	v_mov_b32_e32 v4, v2
	v_mov_b32_e32 v5, v2
	v_mov_b32_e32 v6, v2
	v_mov_b32_e32 v7, v2
	v_mov_b32_e32 v8, v2
	v_mov_b32_e32 v9, v2
	v_mov_b32_e32 v10, v2
	v_mov_b32_e32 v11, v2
	v_mov_b32_e32 v12, v2
	v_mov_b32_e32 v13, v2
	v_mov_b32_e32 v14, v2
	v_mov_b32_e32 v15, v2
	v_mov_b32_e32 v16, v2
	v_mov_b32_e32 v17, v2
	v_mov_b32_e32 v18, v2
	v_mov_b32_e32 v19, v2
	v_mov_b32_e32 v20, v2
	v_mov_b32_e32 v21, v2
	v_mov_b32_e32 v22, v2
	v_mov_b32_e32 v23, v2
	v_mov_b32_e32 v24, v2
	v_mov_b32_e32 v25, v2
	v_mov_b32_e32 v26, v2
	v_mov_b32_e32 v27, v2
	v_mov_b32_e32 v28, v2
	v_mov_b32_e32 v29, v2
	v_mov_b32_e32 v30, v2
	v_mov_b32_e32 v31, v2
	v_mov_b32_e32 v32, v2
	v_mov_b32_e32 v33, v2
	v_mov_b32_e32 v34, v2
	v_mov_b32_e32 v35, v2
	v_mov_b32_e32 v36, v2
	v_mov_b32_e32 v37, v2
	s_waitcnt lgkmcnt(0)
	s_barrier
	v_lshl_add_u64 v[134:135], v[50:51], 0, s[10:11]
	v_add_co_u32_e32 v136, vcc, s93, v134
	s_nop 1
	v_addc_co_u32_e32 v137, vcc, 0, v135, vcc
	v_add_co_u32_e32 v138, vcc, s94, v134
	s_nop 1
	v_addc_co_u32_e32 v139, vcc, 0, v135, vcc
	v_add_co_u32_e32 v140, vcc, s95, v134
	s_nop 1
	v_addc_co_u32_e32 v141, vcc, 0, v135, vcc
	global_load_dwordx4 v[64:67], v[134:135], off nt
	global_load_dwordx4 v[104:107], v[136:137], off nt
	global_load_dwordx4 v[108:111], v[138:139], off nt
	global_load_dwordx4 v[112:115], v[140:141], off nt
	s_add_u32 s10, s10, 0x24000
	s_addc_u32 s11, s11, 0
	s_mov_b32 s46, 16
.LBB0_211:
	v_lshl_add_u64 v[134:135], v[50:51], 0, s[10:11]
	v_add_co_u32_e32 v136, vcc, s93, v134
	s_nop 1
	v_addc_co_u32_e32 v137, vcc, 0, v135, vcc
	v_add_co_u32_e32 v138, vcc, s94, v134
	s_nop 1
	v_addc_co_u32_e32 v139, vcc, 0, v135, vcc
	v_add_co_u32_e32 v140, vcc, s95, v134
	s_nop 1
	v_addc_co_u32_e32 v141, vcc, 0, v135, vcc
	global_load_dwordx4 v[180:183], v[134:135], off nt
	global_load_dwordx4 v[184:187], v[136:137], off nt
	global_load_dwordx4 v[188:191], v[138:139], off nt
	global_load_dwordx4 v[192:195], v[140:141], off nt
	s_add_u32 s10, s10, 0x24000
	s_addc_u32 s11, s11, 0
	v_mov_b32_e32 v46, s13
	ds_read_b128 v[68:71], v46
	ds_read_b128 v[72:75], v46 offset:512
	ds_read_b128 v[76:79], v46 offset:1024
	ds_read_b128 v[80:83], v46 offset:1536
	ds_read_b128 v[84:87], v46 offset:2048
	ds_read_b128 v[88:91], v46 offset:2560
	ds_read_b128 v[92:95], v46 offset:3072
	ds_read_b128 v[96:99], v46 offset:3584
	ds_read_b128 v[100:103], v46 offset:4096
	s_add_i32 s13, s13, 16
	s_waitcnt lgkmcnt(0)
	s_waitcnt vmcnt(4)
	v_pk_fma_f32 v[34:35], v[64:65], v[68:69], v[34:35] op_sel_hi:[1,0,1]
	v_pk_fma_f32 v[36:37], v[66:67], v[68:69], v[36:37] op_sel_hi:[1,0,1]
	v_pk_fma_f32 v[30:31], v[64:65], v[72:73], v[30:31] op_sel_hi:[1,0,1]
	v_pk_fma_f32 v[32:33], v[66:67], v[72:73], v[32:33] op_sel_hi:[1,0,1]
	v_pk_fma_f32 v[26:27], v[64:65], v[76:77], v[26:27] op_sel_hi:[1,0,1]
	v_pk_fma_f32 v[28:29], v[66:67], v[76:77], v[28:29] op_sel_hi:[1,0,1]
	v_pk_fma_f32 v[22:23], v[64:65], v[80:81], v[22:23] op_sel_hi:[1,0,1]
	v_pk_fma_f32 v[24:25], v[66:67], v[80:81], v[24:25] op_sel_hi:[1,0,1]
	v_pk_fma_f32 v[18:19], v[64:65], v[84:85], v[18:19] op_sel_hi:[1,0,1]
	v_pk_fma_f32 v[20:21], v[66:67], v[84:85], v[20:21] op_sel_hi:[1,0,1]
	v_pk_fma_f32 v[14:15], v[64:65], v[88:89], v[14:15] op_sel_hi:[1,0,1]
	v_pk_fma_f32 v[16:17], v[66:67], v[88:89], v[16:17] op_sel_hi:[1,0,1]
	v_pk_fma_f32 v[10:11], v[64:65], v[92:93], v[10:11] op_sel_hi:[1,0,1]
	v_pk_fma_f32 v[12:13], v[66:67], v[92:93], v[12:13] op_sel_hi:[1,0,1]
	v_pk_fma_f32 v[6:7], v[64:65], v[96:97], v[6:7] op_sel_hi:[1,0,1]
	v_pk_fma_f32 v[8:9], v[66:67], v[96:97], v[8:9] op_sel_hi:[1,0,1]
	v_pk_fma_f32 v[2:3], v[64:65], v[100:101], v[2:3] op_sel_hi:[1,0,1]
	v_pk_fma_f32 v[4:5], v[66:67], v[100:101], v[4:5] op_sel_hi:[1,0,1]
	v_pk_fma_f32 v[34:35], v[104:105], v[68:69], v[34:35] op_sel:[0,1,0]
	v_pk_fma_f32 v[36:37], v[106:107], v[68:69], v[36:37] op_sel:[0,1,0]
	v_pk_fma_f32 v[30:31], v[104:105], v[72:73], v[30:31] op_sel:[0,1,0]
	v_pk_fma_f32 v[32:33], v[106:107], v[72:73], v[32:33] op_sel:[0,1,0]
	v_pk_fma_f32 v[26:27], v[104:105], v[76:77], v[26:27] op_sel:[0,1,0]
	v_pk_fma_f32 v[28:29], v[106:107], v[76:77], v[28:29] op_sel:[0,1,0]
	v_pk_fma_f32 v[22:23], v[104:105], v[80:81], v[22:23] op_sel:[0,1,0]
	v_pk_fma_f32 v[24:25], v[106:107], v[80:81], v[24:25] op_sel:[0,1,0]
	v_pk_fma_f32 v[18:19], v[104:105], v[84:85], v[18:19] op_sel:[0,1,0]
	v_pk_fma_f32 v[20:21], v[106:107], v[84:85], v[20:21] op_sel:[0,1,0]
	v_pk_fma_f32 v[14:15], v[104:105], v[88:89], v[14:15] op_sel:[0,1,0]
	v_pk_fma_f32 v[16:17], v[106:107], v[88:89], v[16:17] op_sel:[0,1,0]
	v_pk_fma_f32 v[10:11], v[104:105], v[92:93], v[10:11] op_sel:[0,1,0]
	v_pk_fma_f32 v[12:13], v[106:107], v[92:93], v[12:13] op_sel:[0,1,0]
	v_pk_fma_f32 v[6:7], v[104:105], v[96:97], v[6:7] op_sel:[0,1,0]
	v_pk_fma_f32 v[8:9], v[106:107], v[96:97], v[8:9] op_sel:[0,1,0]
	v_pk_fma_f32 v[2:3], v[104:105], v[100:101], v[2:3] op_sel:[0,1,0]
	v_pk_fma_f32 v[4:5], v[106:107], v[100:101], v[4:5] op_sel:[0,1,0]
	v_pk_fma_f32 v[34:35], v[108:109], v[70:71], v[34:35] op_sel_hi:[1,0,1]
; #define NT_LD4(ptr) __builtin_nontemporal_load((const f32x4v*)(ptr))
; DI void mods_partial(const Params& p, char* wsb, int it, char* lds) {
;     ...
; #pragma unroll 4
;   for (int k = 0; k < 128; ++k) {
;     const f32x4v wq = NT_LD4(w + (size_t)k * 9216);
;     const float4 wv = make_float4(wq[0], wq[1], wq[2], wq[3]);
; #pragma unroll
;     for (int r = 0; r < 9; ++r) {
;       float sv = s[r * 128 + k];
;       acc[r][0] += sv * wv.x; acc[r][1] += sv * wv.y; acc[r][2] += sv * wv.z; acc[r][3] += sv * wv.w;
;     }
;   }
	v_pk_fma_f32 v[36:37], v[110:111], v[70:71], v[36:37] op_sel_hi:[1,0,1]
	v_pk_fma_f32 v[30:31], v[108:109], v[74:75], v[30:31] op_sel_hi:[1,0,1]
	v_pk_fma_f32 v[32:33], v[110:111], v[74:75], v[32:33] op_sel_hi:[1,0,1]
	v_pk_fma_f32 v[26:27], v[108:109], v[78:79], v[26:27] op_sel_hi:[1,0,1]
	v_pk_fma_f32 v[28:29], v[110:111], v[78:79], v[28:29] op_sel_hi:[1,0,1]
	v_pk_fma_f32 v[22:23], v[108:109], v[82:83], v[22:23] op_sel_hi:[1,0,1]
	v_pk_fma_f32 v[24:25], v[110:111], v[82:83], v[24:25] op_sel_hi:[1,0,1]
	v_pk_fma_f32 v[18:19], v[108:109], v[86:87], v[18:19] op_sel_hi:[1,0,1]
	v_pk_fma_f32 v[20:21], v[110:111], v[86:87], v[20:21] op_sel_hi:[1,0,1]
	v_pk_fma_f32 v[14:15], v[108:109], v[90:91], v[14:15] op_sel_hi:[1,0,1]
	v_pk_fma_f32 v[16:17], v[110:111], v[90:91], v[16:17] op_sel_hi:[1,0,1]
	v_pk_fma_f32 v[10:11], v[108:109], v[94:95], v[10:11] op_sel_hi:[1,0,1]
	v_pk_fma_f32 v[12:13], v[110:111], v[94:95], v[12:13] op_sel_hi:[1,0,1]
	v_pk_fma_f32 v[6:7], v[108:109], v[98:99], v[6:7] op_sel_hi:[1,0,1]
	v_pk_fma_f32 v[8:9], v[110:111], v[98:99], v[8:9] op_sel_hi:[1,0,1]
	v_pk_fma_f32 v[2:3], v[108:109], v[102:103], v[2:3] op_sel_hi:[1,0,1]
	v_pk_fma_f32 v[4:5], v[110:111], v[102:103], v[4:5] op_sel_hi:[1,0,1]
	v_pk_fma_f32 v[34:35], v[112:113], v[70:71], v[34:35] op_sel:[0,1,0]
	v_pk_fma_f32 v[36:37], v[114:115], v[70:71], v[36:37] op_sel:[0,1,0]
	v_pk_fma_f32 v[30:31], v[112:113], v[74:75], v[30:31] op_sel:[0,1,0]
	v_pk_fma_f32 v[32:33], v[114:115], v[74:75], v[32:33] op_sel:[0,1,0]
	v_pk_fma_f32 v[26:27], v[112:113], v[78:79], v[26:27] op_sel:[0,1,0]
	v_pk_fma_f32 v[28:29], v[114:115], v[78:79], v[28:29] op_sel:[0,1,0]
	v_pk_fma_f32 v[22:23], v[112:113], v[82:83], v[22:23] op_sel:[0,1,0]
	v_pk_fma_f32 v[24:25], v[114:115], v[82:83], v[24:25] op_sel:[0,1,0]
	v_pk_fma_f32 v[18:19], v[112:113], v[86:87], v[18:19] op_sel:[0,1,0]
	v_pk_fma_f32 v[20:21], v[114:115], v[86:87], v[20:21] op_sel:[0,1,0]
	v_pk_fma_f32 v[14:15], v[112:113], v[90:91], v[14:15] op_sel:[0,1,0]
	v_pk_fma_f32 v[16:17], v[114:115], v[90:91], v[16:17] op_sel:[0,1,0]
	v_pk_fma_f32 v[10:11], v[112:113], v[94:95], v[10:11] op_sel:[0,1,0]
	v_pk_fma_f32 v[12:13], v[114:115], v[94:95], v[12:13] op_sel:[0,1,0]
	v_pk_fma_f32 v[6:7], v[112:113], v[98:99], v[6:7] op_sel:[0,1,0]
	v_pk_fma_f32 v[8:9], v[114:115], v[98:99], v[8:9] op_sel:[0,1,0]
	v_pk_fma_f32 v[2:3], v[112:113], v[102:103], v[2:3] op_sel:[0,1,0]
	v_pk_fma_f32 v[4:5], v[114:115], v[102:103], v[4:5] op_sel:[0,1,0]
	s_cmp_eq_u32 s46, 1
	s_cbranch_scc1 .Lmods_last
	v_lshl_add_u64 v[134:135], v[50:51], 0, s[10:11]
	v_add_co_u32_e32 v136, vcc, s93, v134
	s_nop 1
	v_addc_co_u32_e32 v137, vcc, 0, v135, vcc
	v_add_co_u32_e32 v138, vcc, s94, v134
	s_nop 1
	v_addc_co_u32_e32 v139, vcc, 0, v135, vcc
	v_add_co_u32_e32 v140, vcc, s95, v134
	s_nop 1
	v_addc_co_u32_e32 v141, vcc, 0, v135, vcc
	global_load_dwordx4 v[64:67], v[134:135], off nt
	global_load_dwordx4 v[104:107], v[136:137], off nt
	global_load_dwordx4 v[108:111], v[138:139], off nt
	global_load_dwordx4 v[112:115], v[140:141], off nt
	s_add_u32 s10, s10, 0x24000
	s_addc_u32 s11, s11, 0
	v_mov_b32_e32 v46, s13
	ds_read_b128 v[68:71], v46
	ds_read_b128 v[72:75], v46 offset:512
	ds_read_b128 v[76:79], v46 offset:1024
	ds_read_b128 v[80:83], v46 offset:1536
	ds_read_b128 v[84:87], v46 offset:2048
	ds_read_b128 v[88:91], v46 offset:2560
	ds_read_b128 v[92:95], v46 offset:3072
	ds_read_b128 v[96:99], v46 offset:3584
	ds_read_b128 v[100:103], v46 offset:4096
	s_add_i32 s13, s13, 16
	s_waitcnt lgkmcnt(0)
	s_waitcnt vmcnt(4)
	v_pk_fma_f32 v[34:35], v[180:181], v[68:69], v[34:35] op_sel_hi:[1,0,1]
	v_pk_fma_f32 v[36:37], v[182:183], v[68:69], v[36:37] op_sel_hi:[1,0,1]
	v_pk_fma_f32 v[30:31], v[180:181], v[72:73], v[30:31] op_sel_hi:[1,0,1]
	v_pk_fma_f32 v[32:33], v[182:183], v[72:73], v[32:33] op_sel_hi:[1,0,1]
	v_pk_fma_f32 v[26:27], v[180:181], v[76:77], v[26:27] op_sel_hi:[1,0,1]
	v_pk_fma_f32 v[28:29], v[182:183], v[76:77], v[28:29] op_sel_hi:[1,0,1]
	v_pk_fma_f32 v[22:23], v[180:181], v[80:81], v[22:23] op_sel_hi:[1,0,1]
	v_pk_fma_f32 v[24:25], v[182:183], v[80:81], v[24:25] op_sel_hi:[1,0,1]
	v_pk_fma_f32 v[18:19], v[180:181], v[84:85], v[18:19] op_sel_hi:[1,0,1]
	v_pk_fma_f32 v[20:21], v[182:183], v[84:85], v[20:21] op_sel_hi:[1,0,1]
	v_pk_fma_f32 v[14:15], v[180:181], v[88:89], v[14:15] op_sel_hi:[1,0,1]
	v_pk_fma_f32 v[16:17], v[182:183], v[88:89], v[16:17] op_sel_hi:[1,0,1]
	v_pk_fma_f32 v[10:11], v[180:181], v[92:93], v[10:11] op_sel_hi:[1,0,1]
	v_pk_fma_f32 v[12:13], v[182:183], v[92:93], v[12:13] op_sel_hi:[1,0,1]
	v_pk_fma_f32 v[6:7], v[180:181], v[96:97], v[6:7] op_sel_hi:[1,0,1]
	v_pk_fma_f32 v[8:9], v[182:183], v[96:97], v[8:9] op_sel_hi:[1,0,1]
	v_pk_fma_f32 v[2:3], v[180:181], v[100:101], v[2:3] op_sel_hi:[1,0,1]
	v_pk_fma_f32 v[4:5], v[182:183], v[100:101], v[4:5] op_sel_hi:[1,0,1]
	v_pk_fma_f32 v[34:35], v[184:185], v[68:69], v[34:35] op_sel:[0,1,0]
	v_pk_fma_f32 v[36:37], v[186:187], v[68:69], v[36:37] op_sel:[0,1,0]
	v_pk_fma_f32 v[30:31], v[184:185], v[72:73], v[30:31] op_sel:[0,1,0]
	v_pk_fma_f32 v[32:33], v[186:187], v[72:73], v[32:33] op_sel:[0,1,0]
	v_pk_fma_f32 v[26:27], v[184:185], v[76:77], v[26:27] op_sel:[0,1,0]
	v_pk_fma_f32 v[28:29], v[186:187], v[76:77], v[28:29] op_sel:[0,1,0]
	v_pk_fma_f32 v[22:23], v[184:185], v[80:81], v[22:23] op_sel:[0,1,0]
	v_pk_fma_f32 v[24:25], v[186:187], v[80:81], v[24:25] op_sel:[0,1,0]
	v_pk_fma_f32 v[18:19], v[184:185], v[84:85], v[18:19] op_sel:[0,1,0]
	v_pk_fma_f32 v[20:21], v[186:187], v[84:85], v[20:21] op_sel:[0,1,0]
	v_pk_fma_f32 v[14:15], v[184:185], v[88:89], v[14:15] op_sel:[0,1,0]
; #define NT_LD4(ptr) __builtin_nontemporal_load((const f32x4v*)(ptr))
; DI void mods_partial(const Params& p, char* wsb, int it, char* lds) {
;     ...
; #pragma unroll 4
;   for (int k = 0; k < 128; ++k) {
;     const f32x4v wq = NT_LD4(w + (size_t)k * 9216);
;     const float4 wv = make_float4(wq[0], wq[1], wq[2], wq[3]);
; #pragma unroll
;     for (int r = 0; r < 9; ++r) {
;       float sv = s[r * 128 + k];
;       acc[r][0] += sv * wv.x; acc[r][1] += sv * wv.y; acc[r][2] += sv * wv.z; acc[r][3] += sv * wv.w;
;     }
;   }
	v_pk_fma_f32 v[16:17], v[186:187], v[88:89], v[16:17] op_sel:[0,1,0]
	v_pk_fma_f32 v[10:11], v[184:185], v[92:93], v[10:11] op_sel:[0,1,0]
	v_pk_fma_f32 v[12:13], v[186:187], v[92:93], v[12:13] op_sel:[0,1,0]
	v_pk_fma_f32 v[6:7], v[184:185], v[96:97], v[6:7] op_sel:[0,1,0]
	v_pk_fma_f32 v[8:9], v[186:187], v[96:97], v[8:9] op_sel:[0,1,0]
	v_pk_fma_f32 v[2:3], v[184:185], v[100:101], v[2:3] op_sel:[0,1,0]
	v_pk_fma_f32 v[4:5], v[186:187], v[100:101], v[4:5] op_sel:[0,1,0]
	v_pk_fma_f32 v[34:35], v[188:189], v[70:71], v[34:35] op_sel_hi:[1,0,1]
	v_pk_fma_f32 v[36:37], v[190:191], v[70:71], v[36:37] op_sel_hi:[1,0,1]
	v_pk_fma_f32 v[30:31], v[188:189], v[74:75], v[30:31] op_sel_hi:[1,0,1]
	v_pk_fma_f32 v[32:33], v[190:191], v[74:75], v[32:33] op_sel_hi:[1,0,1]
	v_pk_fma_f32 v[26:27], v[188:189], v[78:79], v[26:27] op_sel_hi:[1,0,1]
	v_pk_fma_f32 v[28:29], v[190:191], v[78:79], v[28:29] op_sel_hi:[1,0,1]
	v_pk_fma_f32 v[22:23], v[188:189], v[82:83], v[22:23] op_sel_hi:[1,0,1]
	v_pk_fma_f32 v[24:25], v[190:191], v[82:83], v[24:25] op_sel_hi:[1,0,1]
	v_pk_fma_f32 v[18:19], v[188:189], v[86:87], v[18:19] op_sel_hi:[1,0,1]
	v_pk_fma_f32 v[20:21], v[190:191], v[86:87], v[20:21] op_sel_hi:[1,0,1]
	v_pk_fma_f32 v[14:15], v[188:189], v[90:91], v[14:15] op_sel_hi:[1,0,1]
	v_pk_fma_f32 v[16:17], v[190:191], v[90:91], v[16:17] op_sel_hi:[1,0,1]
	v_pk_fma_f32 v[10:11], v[188:189], v[94:95], v[10:11] op_sel_hi:[1,0,1]
	v_pk_fma_f32 v[12:13], v[190:191], v[94:95], v[12:13] op_sel_hi:[1,0,1]
	v_pk_fma_f32 v[6:7], v[188:189], v[98:99], v[6:7] op_sel_hi:[1,0,1]
	v_pk_fma_f32 v[8:9], v[190:191], v[98:99], v[8:9] op_sel_hi:[1,0,1]
	v_pk_fma_f32 v[2:3], v[188:189], v[102:103], v[2:3] op_sel_hi:[1,0,1]
	v_pk_fma_f32 v[4:5], v[190:191], v[102:103], v[4:5] op_sel_hi:[1,0,1]
	v_pk_fma_f32 v[34:35], v[192:193], v[70:71], v[34:35] op_sel:[0,1,0]
	v_pk_fma_f32 v[36:37], v[194:195], v[70:71], v[36:37] op_sel:[0,1,0]
	v_pk_fma_f32 v[30:31], v[192:193], v[74:75], v[30:31] op_sel:[0,1,0]
	v_pk_fma_f32 v[32:33], v[194:195], v[74:75], v[32:33] op_sel:[0,1,0]
	v_pk_fma_f32 v[26:27], v[192:193], v[78:79], v[26:27] op_sel:[0,1,0]
	v_pk_fma_f32 v[28:29], v[194:195], v[78:79], v[28:29] op_sel:[0,1,0]
	v_pk_fma_f32 v[22:23], v[192:193], v[82:83], v[22:23] op_sel:[0,1,0]
	v_pk_fma_f32 v[24:25], v[194:195], v[82:83], v[24:25] op_sel:[0,1,0]
	v_pk_fma_f32 v[18:19], v[192:193], v[86:87], v[18:19] op_sel:[0,1,0]
	v_pk_fma_f32 v[20:21], v[194:195], v[86:87], v[20:21] op_sel:[0,1,0]
	v_pk_fma_f32 v[14:15], v[192:193], v[90:91], v[14:15] op_sel:[0,1,0]
	v_pk_fma_f32 v[16:17], v[194:195], v[90:91], v[16:17] op_sel:[0,1,0]
	v_pk_fma_f32 v[10:11], v[192:193], v[94:95], v[10:11] op_sel:[0,1,0]
	v_pk_fma_f32 v[12:13], v[194:195], v[94:95], v[12:13] op_sel:[0,1,0]
	v_pk_fma_f32 v[6:7], v[192:193], v[98:99], v[6:7] op_sel:[0,1,0]
	v_pk_fma_f32 v[8:9], v[194:195], v[98:99], v[8:9] op_sel:[0,1,0]
	v_pk_fma_f32 v[2:3], v[192:193], v[102:103], v[2:3] op_sel:[0,1,0]
	v_pk_fma_f32 v[4:5], v[194:195], v[102:103], v[4:5] op_sel:[0,1,0]
	s_sub_u32 s46, s46, 1
	s_branch .LBB0_211
; #define NT_LD4(ptr) __builtin_nontemporal_load((const f32x4v*)(ptr))
; DI void mods_partial(const Params& p, char* wsb, int it, char* lds) {
;     ...
; #pragma unroll 4
;   for (int k = 0; k < 128; ++k) {
;     const f32x4v wq = NT_LD4(w + (size_t)k * 9216);
;     const float4 wv = make_float4(wq[0], wq[1], wq[2], wq[3]);
; #pragma unroll
;     for (int r = 0; r < 9; ++r) {
;       float sv = s[r * 128 + k];
;       acc[r][0] += sv * wv.x; acc[r][1] += sv * wv.y; acc[r][2] += sv * wv.z; acc[r][3] += sv * wv.w;
;     }
;   }
;   float* mp = (float*)(wsb + OFF_MODP);
; #pragma unroll
;   for (int r = 0; r < 9; ++r) {
;     float4 o = make_float4(acc[r][0], acc[r][1], acc[r][2], acc[r][3]);
;     *(float4*)(mp + ((size_t)((kc * 4 + layer) * 9 + r)) * 9216 + cgp * 1024 + tid * 4) = o;
;   }
;   __syncthreads();
.Lmods_last:
	v_mov_b32_e32 v46, s13
	ds_read_b128 v[68:71], v46
	ds_read_b128 v[72:75], v46 offset:512
	ds_read_b128 v[76:79], v46 offset:1024
	ds_read_b128 v[80:83], v46 offset:1536
	ds_read_b128 v[84:87], v46 offset:2048
	ds_read_b128 v[88:91], v46 offset:2560
	ds_read_b128 v[92:95], v46 offset:3072
	ds_read_b128 v[96:99], v46 offset:3584
	ds_read_b128 v[100:103], v46 offset:4096
	s_add_i32 s13, s13, 16
	s_waitcnt lgkmcnt(0)
	s_waitcnt vmcnt(0)
	v_pk_fma_f32 v[34:35], v[180:181], v[68:69], v[34:35] op_sel_hi:[1,0,1]
	v_pk_fma_f32 v[36:37], v[182:183], v[68:69], v[36:37] op_sel_hi:[1,0,1]
	v_pk_fma_f32 v[30:31], v[180:181], v[72:73], v[30:31] op_sel_hi:[1,0,1]
	v_pk_fma_f32 v[32:33], v[182:183], v[72:73], v[32:33] op_sel_hi:[1,0,1]
	v_pk_fma_f32 v[26:27], v[180:181], v[76:77], v[26:27] op_sel_hi:[1,0,1]
	v_pk_fma_f32 v[28:29], v[182:183], v[76:77], v[28:29] op_sel_hi:[1,0,1]
	v_pk_fma_f32 v[22:23], v[180:181], v[80:81], v[22:23] op_sel_hi:[1,0,1]
	v_pk_fma_f32 v[24:25], v[182:183], v[80:81], v[24:25] op_sel_hi:[1,0,1]
	v_pk_fma_f32 v[18:19], v[180:181], v[84:85], v[18:19] op_sel_hi:[1,0,1]
	v_pk_fma_f32 v[20:21], v[182:183], v[84:85], v[20:21] op_sel_hi:[1,0,1]
	v_pk_fma_f32 v[14:15], v[180:181], v[88:89], v[14:15] op_sel_hi:[1,0,1]
	v_pk_fma_f32 v[16:17], v[182:183], v[88:89], v[16:17] op_sel_hi:[1,0,1]
	v_pk_fma_f32 v[10:11], v[180:181], v[92:93], v[10:11] op_sel_hi:[1,0,1]
	v_pk_fma_f32 v[12:13], v[182:183], v[92:93], v[12:13] op_sel_hi:[1,0,1]
	v_pk_fma_f32 v[6:7], v[180:181], v[96:97], v[6:7] op_sel_hi:[1,0,1]
	v_pk_fma_f32 v[8:9], v[182:183], v[96:97], v[8:9] op_sel_hi:[1,0,1]
	v_pk_fma_f32 v[2:3], v[180:181], v[100:101], v[2:3] op_sel_hi:[1,0,1]
	v_pk_fma_f32 v[4:5], v[182:183], v[100:101], v[4:5] op_sel_hi:[1,0,1]
	v_pk_fma_f32 v[34:35], v[184:185], v[68:69], v[34:35] op_sel:[0,1,0]
	v_pk_fma_f32 v[36:37], v[186:187], v[68:69], v[36:37] op_sel:[0,1,0]
	v_pk_fma_f32 v[30:31], v[184:185], v[72:73], v[30:31] op_sel:[0,1,0]
	v_pk_fma_f32 v[32:33], v[186:187], v[72:73], v[32:33] op_sel:[0,1,0]
	v_pk_fma_f32 v[26:27], v[184:185], v[76:77], v[26:27] op_sel:[0,1,0]
	v_pk_fma_f32 v[28:29], v[186:187], v[76:77], v[28:29] op_sel:[0,1,0]
	v_pk_fma_f32 v[22:23], v[184:185], v[80:81], v[22:23] op_sel:[0,1,0]
	v_pk_fma_f32 v[24:25], v[186:187], v[80:81], v[24:25] op_sel:[0,1,0]
	v_pk_fma_f32 v[18:19], v[184:185], v[84:85], v[18:19] op_sel:[0,1,0]
	v_pk_fma_f32 v[20:21], v[186:187], v[84:85], v[20:21] op_sel:[0,1,0]
	v_pk_fma_f32 v[14:15], v[184:185], v[88:89], v[14:15] op_sel:[0,1,0]
	v_pk_fma_f32 v[16:17], v[186:187], v[88:89], v[16:17] op_sel:[0,1,0]
	v_pk_fma_f32 v[10:11], v[184:185], v[92:93], v[10:11] op_sel:[0,1,0]
	v_pk_fma_f32 v[12:13], v[186:187], v[92:93], v[12:13] op_sel:[0,1,0]
	v_pk_fma_f32 v[6:7], v[184:185], v[96:97], v[6:7] op_sel:[0,1,0]
	v_pk_fma_f32 v[8:9], v[186:187], v[96:97], v[8:9] op_sel:[0,1,0]
	v_pk_fma_f32 v[2:3], v[184:185], v[100:101], v[2:3] op_sel:[0,1,0]
	v_pk_fma_f32 v[4:5], v[186:187], v[100:101], v[4:5] op_sel:[0,1,0]
	v_pk_fma_f32 v[34:35], v[188:189], v[70:71], v[34:35] op_sel_hi:[1,0,1]
	v_pk_fma_f32 v[36:37], v[190:191], v[70:71], v[36:37] op_sel_hi:[1,0,1]
	v_pk_fma_f32 v[30:31], v[188:189], v[74:75], v[30:31] op_sel_hi:[1,0,1]
	v_pk_fma_f32 v[32:33], v[190:191], v[74:75], v[32:33] op_sel_hi:[1,0,1]
	v_pk_fma_f32 v[26:27], v[188:189], v[78:79], v[26:27] op_sel_hi:[1,0,1]
	v_pk_fma_f32 v[28:29], v[190:191], v[78:79], v[28:29] op_sel_hi:[1,0,1]
	v_pk_fma_f32 v[22:23], v[188:189], v[82:83], v[22:23] op_sel_hi:[1,0,1]
	v_pk_fma_f32 v[24:25], v[190:191], v[82:83], v[24:25] op_sel_hi:[1,0,1]
	v_pk_fma_f32 v[18:19], v[188:189], v[86:87], v[18:19] op_sel_hi:[1,0,1]
	v_pk_fma_f32 v[20:21], v[190:191], v[86:87], v[20:21] op_sel_hi:[1,0,1]
	v_pk_fma_f32 v[14:15], v[188:189], v[90:91], v[14:15] op_sel_hi:[1,0,1]
	v_pk_fma_f32 v[16:17], v[190:191], v[90:91], v[16:17] op_sel_hi:[1,0,1]
	v_pk_fma_f32 v[10:11], v[188:189], v[94:95], v[10:11] op_sel_hi:[1,0,1]
	v_pk_fma_f32 v[12:13], v[190:191], v[94:95], v[12:13] op_sel_hi:[1,0,1]
	v_pk_fma_f32 v[6:7], v[188:189], v[98:99], v[6:7] op_sel_hi:[1,0,1]
	v_pk_fma_f32 v[8:9], v[190:191], v[98:99], v[8:9] op_sel_hi:[1,0,1]
	v_pk_fma_f32 v[2:3], v[188:189], v[102:103], v[2:3] op_sel_hi:[1,0,1]
	v_pk_fma_f32 v[4:5], v[190:191], v[102:103], v[4:5] op_sel_hi:[1,0,1]
	v_pk_fma_f32 v[34:35], v[192:193], v[70:71], v[34:35] op_sel:[0,1,0]
	v_pk_fma_f32 v[36:37], v[194:195], v[70:71], v[36:37] op_sel:[0,1,0]
	v_pk_fma_f32 v[30:31], v[192:193], v[74:75], v[30:31] op_sel:[0,1,0]
	v_pk_fma_f32 v[32:33], v[194:195], v[74:75], v[32:33] op_sel:[0,1,0]
	v_pk_fma_f32 v[26:27], v[192:193], v[78:79], v[26:27] op_sel:[0,1,0]
	v_pk_fma_f32 v[28:29], v[194:195], v[78:79], v[28:29] op_sel:[0,1,0]
	v_pk_fma_f32 v[22:23], v[192:193], v[82:83], v[22:23] op_sel:[0,1,0]
	v_pk_fma_f32 v[24:25], v[194:195], v[82:83], v[24:25] op_sel:[0,1,0]
	v_pk_fma_f32 v[18:19], v[192:193], v[86:87], v[18:19] op_sel:[0,1,0]
	v_pk_fma_f32 v[20:21], v[194:195], v[86:87], v[20:21] op_sel:[0,1,0]
	v_pk_fma_f32 v[14:15], v[192:193], v[90:91], v[14:15] op_sel:[0,1,0]
	v_pk_fma_f32 v[16:17], v[194:195], v[90:91], v[16:17] op_sel:[0,1,0]
	v_pk_fma_f32 v[10:11], v[192:193], v[94:95], v[10:11] op_sel:[0,1,0]
	v_pk_fma_f32 v[12:13], v[194:195], v[94:95], v[12:13] op_sel:[0,1,0]
	v_pk_fma_f32 v[6:7], v[192:193], v[98:99], v[6:7] op_sel:[0,1,0]
	v_pk_fma_f32 v[8:9], v[194:195], v[98:99], v[8:9] op_sel:[0,1,0]
	v_pk_fma_f32 v[2:3], v[192:193], v[102:103], v[2:3] op_sel:[0,1,0]
	v_pk_fma_f32 v[4:5], v[194:195], v[102:103], v[4:5] op_sel:[0,1,0]
	s_lshl_b32 s10, s12, 2
	s_add_i32 s4, s10, s4
	v_lshl_add_u64 v[50:51], s[8:9], 2, v[42:43]
	s_mul_i32 s4, s4, 9
	v_lshl_add_u64 v[48:49], v[48:49], 2, v[50:51]
	v_mad_i64_i32 v[50:51], s[8:9], s4, v63, v[48:49]
	s_add_i32 s8, s4, 1
	global_store_dwordx4 v[50:51], v[34:37], off
	s_mov_b64 s[40:41], -1
	s_nop 0
	v_mad_i64_i32 v[34:35], s[8:9], s8, v63, v[48:49]
	s_add_i32 s8, s4, 2
	global_store_dwordx4 v[34:35], v[30:33], off
	s_nop 1
	v_mad_i64_i32 v[30:31], s[8:9], s8, v63, v[48:49]
	s_add_i32 s8, s4, 3
	global_store_dwordx4 v[30:31], v[26:29], off
	s_nop 1
	v_mad_i64_i32 v[26:27], s[8:9], s8, v63, v[48:49]
	s_add_i32 s8, s4, 4
	global_store_dwordx4 v[26:27], v[22:25], off
	s_nop 1
	v_mad_i64_i32 v[22:23], s[8:9], s8, v63, v[48:49]
	s_add_i32 s8, s4, 5
	global_store_dwordx4 v[22:23], v[18:21], off
	s_nop 1
	v_mad_i64_i32 v[18:19], s[8:9], s8, v63, v[48:49]
	s_add_i32 s8, s4, 6
	global_store_dwordx4 v[18:19], v[14:17], off
	s_nop 1
	v_mad_i64_i32 v[14:15], s[8:9], s8, v63, v[48:49]
	s_add_i32 s8, s4, 7
	global_store_dwordx4 v[14:15], v[10:13], off
	s_add_i32 s4, s4, 8
	s_nop 0
	v_mad_i64_i32 v[10:11], s[8:9], s8, v63, v[48:49]
	global_store_dwordx4 v[10:11], v[6:9], off
	s_nop 1
	v_mad_i64_i32 v[6:7], s[8:9], s4, v63, v[48:49]
	global_store_dwordx4 v[6:7], v[2:5], off
	s_barrier

; #define MFMA(a, b, c) __builtin_amdgcn_mfma_f32_32x32x16_bf16((a), (b), (c), 0, 0, 0)
; DI float bf2f(u16 v) { return __uint_as_float(((unsigned)v) << 16); }
; template <int NB1>
; DI void hyena_item(const Params& p, char* wsb, int layer, int c, char* lds) {
;     ...
; #pragma unroll 1
;         for (int d1o = lo; d1o < hi; d1o += 2) {
; #pragma unroll
;           for (int dk = 0; dk < 4; ++dk) {
;             const int d1 = d1o + (dk >> 1), ks = dk & 1;
;             const unsigned* rp = Rd + (-16 * d1 + 8 * ks);
;             unsigned w[5];
; #pragma unroll
;             for (int q = 0; q < 5; ++q) w[q] = rp[q];
;             union { s16x8 v; unsigned u[4]; } af;
; #pragma unroll
;             for (int q = 0; q < 4; ++q) af.u[q] = __builtin_amdgcn_alignbit(w[q + 1], w[q], sh);
; #pragma unroll
;             for (int j = 0; j < TPW; ++j) {
;               if (!((jmask >> (j & 1)) & 1)) continue;
;               const bool ok = (unsigned)(tt1[j] - d1) < (unsigned)NB1;
;               const int addr = ok ? ub[j] - d1 * 80 + ks * 32 : zaddr;
;               const s16x8 bf = *(const s16x8*)(lds + addr);
;               acc[j] = MFMA(af.v, bf, acc[j]);
;             }
;           }
;         }
;     ...
;         for (int g4 = 0; g4 < 4; ++g4) {
;           const int t0 = 8 * g4 + 4 * h, t = 32 * tt1[j] + t0;
;           const int uidx = (tb[j] * NB1 + tt1[j]) * 40 + t0;
;           const uint2 uu = *(const uint2*)(U + uidx);
;           const uint2 zz = *(const uint2*)(zr + t);
;           const float zm1 = t > 0 ? bf2f(zr[t - 1]) : 0.f;
;           const float zp4 = t + 4 < L ? bf2f(zr[t + 4]) : 0.f;
;           const float zv[6] = {zm1, bf2f((u16)(zz.x & 0xffff)), bf2f((u16)(zz.x >> 16)), bf2f((u16)(zz.y & 0xffff)), bf2f((u16)(zz.y >> 16)), zp4};
;           const float uv[4] = {bf2f((u16)(uu.x & 0xffff)), bf2f((u16)(uu.x >> 16)), bf2f((u16)(uu.y & 0xffff)), bf2f((u16)(uu.y >> 16))};
;           float yv[4];
; #pragma unroll
;           for (int e = 0; e < 4; ++e) {
;             const float xv = w0 * zv[e] + w1 * zv[e + 1] + w2 * zv[e + 2] + bb;
;             yv[e] = xv * (acc[j][4 * g4 + e] + bias * uv[e]);
;           }
;           if (order == 0) *(uint2*)(U + uidx) = make_uint2(pack2(yv[0], yv[1]), pack2(yv[2], yv[3]));
.LBB0_871:
	v_cmp_gt_u32_e32 vcc, 64, v72
	v_add_u32_e32 v246, 1, v73
	v_cmp_gt_u32_e64 s[6:7], 64, v246
	v_add_u32_e32 v213, 0x50, v71
	v_add_u32_e32 v214, 0x1450, v71
	v_add_u32_e32 v215, 0x70, v71
	v_add_u32_e32 v216, 0x1470, v71
	v_cndmask_b32_e32 v213, v212, v213, vcc
	v_cndmask_b32_e64 v214, v212, v214, s[6:7]
	v_cndmask_b32_e32 v215, v212, v215, vcc
	v_cndmask_b32_e64 v216, v212, v216, s[6:7]
	v_cmp_gt_u32_e32 vcc, 64, v73
	v_add_u32_e32 v246, -1, v72
	v_cmp_gt_u32_e64 s[6:7], 64, v246
	v_add_u32_e32 v218, 0x1400, v71
	v_add_u32_e32 v219, 32, v71
	v_add_u32_e32 v220, 0x1420, v71
	v_cndmask_b32_e64 v217, v212, v71, s[6:7]
	v_cndmask_b32_e32 v218, v212, v218, vcc
	v_cndmask_b32_e64 v219, v212, v219, s[6:7]
	v_cndmask_b32_e32 v220, v212, v220, vcc
	v_add_u32_e32 v73, -2, v73
	v_add_u32_e32 v72, -2, v72
	s_add_i32 s8, s8, 2
	ds_read2_b32 v[134:135], v70 offset0:16 offset1:17
	ds_read2_b32 v[138:139], v70 offset0:17 offset1:18
	ds_read2_b32 v[136:137], v70 offset0:19 offset1:20
	ds_read2_b32 v[222:223], v70 offset0:24 offset1:25
	ds_read2_b32 v[226:227], v70 offset0:25 offset1:26
	ds_read2_b32 v[224:225], v70 offset0:27 offset1:28
	ds_read_b128 v[230:233], v213
	ds_read_b128 v[234:237], v214
	ds_read_b128 v[238:241], v215
	ds_read_b128 v[170:173], v216
	s_waitcnt lgkmcnt(4)
	v_alignbit_b32 v134, v138, v134, v66
	v_alignbit_b32 v137, v137, v136, v69
	v_alignbit_b32 v136, v136, v139, v68
	v_alignbit_b32 v135, v139, v135, v67
	v_alignbit_b32 v222, v226, v222, v66
	v_alignbit_b32 v225, v225, v224, v69
	v_alignbit_b32 v224, v224, v227, v68
	v_alignbit_b32 v223, v227, v223, v67
	s_waitcnt lgkmcnt(3)
	v_mfma_f32_32x32x16_bf16 v[50:65], v[134:137], v[230:233], v[50:65]
	s_waitcnt lgkmcnt(2)
	v_mfma_f32_32x32x16_bf16 v[18:33], v[134:137], v[234:237], v[18:33]
	s_waitcnt lgkmcnt(1)
	v_mfma_f32_32x32x16_bf16 v[50:65], v[222:225], v[238:241], v[50:65]
	s_waitcnt lgkmcnt(0)
	v_mfma_f32_32x32x16_bf16 v[18:33], v[222:225], v[170:173], v[18:33]
	ds_read2_b32 v[134:135], v70 offset1:1
	ds_read2_b32 v[138:139], v70 offset0:1 offset1:2
	ds_read2_b32 v[136:137], v70 offset0:3 offset1:4
	ds_read2_b32 v[222:223], v70 offset0:8 offset1:9
	ds_read2_b32 v[226:227], v70 offset0:9 offset1:10
	ds_read2_b32 v[224:225], v70 offset0:11 offset1:12
	ds_read_b128 v[230:233], v217
	ds_read_b128 v[234:237], v218
	ds_read_b128 v[238:241], v219
	ds_read_b128 v[170:173], v220
	s_waitcnt lgkmcnt(4)
	v_alignbit_b32 v134, v138, v134, v66
	v_alignbit_b32 v137, v137, v136, v69
	v_alignbit_b32 v136, v136, v139, v68
	v_alignbit_b32 v135, v139, v135, v67
	v_alignbit_b32 v222, v226, v222, v66
	v_alignbit_b32 v225, v225, v224, v69
	v_alignbit_b32 v224, v224, v227, v68
	v_alignbit_b32 v223, v227, v223, v67
	s_waitcnt lgkmcnt(3)
	v_mfma_f32_32x32x16_bf16 v[50:65], v[134:137], v[230:233], v[50:65]
	s_waitcnt lgkmcnt(2)
	v_mfma_f32_32x32x16_bf16 v[18:33], v[134:137], v[234:237], v[18:33]
	s_waitcnt lgkmcnt(1)
	v_mfma_f32_32x32x16_bf16 v[50:65], v[222:225], v[238:241], v[50:65]
	s_waitcnt lgkmcnt(0)
	v_mfma_f32_32x32x16_bf16 v[18:33], v[222:225], v[170:173], v[18:33]
	v_add_u32_e32 v70, 0xffffff80, v70
	v_add_u32_e32 v71, 0xffffff60, v71
	s_cmp_lt_u32 s8, 62
	s_cbranch_scc1 .LBB0_871
	s_add_i32 s11, s11, s10
	v_add_u32_e32 v70, s11, v149
	v_ashrrev_i32_e32 v71, 31, v70
	v_lshlrev_b64 v[70:71], 12, v[70:71]
	v_lshl_add_u64 v[72:73], s[36:37], 0, v[70:71]
	v_lshl_add_u64 v[140:141], v[74:75], 1, v[72:73]
	global_load_dwordx2 v[136:137], v[140:141], off
	global_load_ushort v246, v[140:141], off offset:8
	ds_read_b64 v[138:139], v148
	v_mov_b32_e32 v135, 0
	v_lshl_add_u64 v[70:71], v[0:1], 1, v[72:73]
	s_and_saveexec_b64 s[6:7], s[48:49]
	s_cbranch_execz .LBB0_874
	global_load_ushort v123, v[70:71], off offset:-2
	s_waitcnt vmcnt(0)
	v_lshlrev_b32_e32 v135, 16, v123
.LBB0_874:
	s_or_b64 exec, exec, s[6:7]
	s_waitcnt vmcnt(1)
	v_and_b32_e32 v170, 0xffff0000, v136
	v_mov_b32_e32 v134, v170
	v_lshlrev_b32_e32 v140, 16, v136
	v_pk_mul_f32 v[134:135], v[128:129], v[134:135]
	v_lshlrev_b32_e32 v171, 16, v137
	v_pk_fma_f32 v[134:135], v[128:129], v[140:141], v[134:135] op_sel:[0,0,1] op_sel_hi:[1,0,0]
	s_waitcnt lgkmcnt(0)
	v_lshlrev_b32_e32 v172, 16, v138
	v_and_b32_e32 v173, 0xffff0000, v138
	v_and_b32_e32 v174, 0xffff0000, v137
	v_mov_b32_e32 v136, v174
	v_pk_fma_f32 v[34:35], v[126:127], v[172:173], v[34:35] op_sel_hi:[0,1,1]
	v_lshlrev_b32_e32 v138, 16, v139
	v_and_b32_e32 v139, 0xffff0000, v139
	v_pk_fma_f32 v[36:37], v[126:127], v[138:139], v[36:37] op_sel_hi:[0,1,1]
	s_mov_b64 s[6:7], -1
	s_and_b64 vcc, exec, s[16:17]
	s_waitcnt vmcnt(0)
	v_mov_b32_e32 v123, v246
	v_and_b32_e32 v175, 16, v123
	v_pk_fma_f32 v[134:135], v[122:123], v[170:171], v[134:135] op_sel_hi:[0,1,1]
	v_pk_mov_b32 v[174:175], v[170:171], v[174:175] op_sel:[1,0]
	v_pk_add_f32 v[134:135], v[124:125], v[134:135] op_sel_hi:[0,1]
	v_pk_mul_f32 v[34:35], v[34:35], v[134:135]
	v_mov_b32_e32 v134, v129
	v_pk_mul_f32 v[140:141], v[128:129], v[174:175] op_sel_hi:[0,1]
	v_lshlrev_b32_e32 v137, 16, v123
	v_pk_fma_f32 v[134:135], v[134:135], v[170:171], v[140:141] op_sel_hi:[0,1,1]
	v_pk_fma_f32 v[134:135], v[122:123], v[136:137], v[134:135] op_sel_hi:[0,1,1]
	v_pk_add_f32 v[134:135], v[124:125], v[134:135] op_sel_hi:[0,1]
	v_pk_mul_f32 v[36:37], v[36:37], v[134:135]
	v_cvt_pk_bf16_f32 v34, v34, v35
	v_cvt_pk_bf16_f32 v35, v36, v37
	s_cbranch_vccz .LBB0_876
	global_store_short v[76:77], v34, off
	global_store_short_d16_hi v[76:77], v34, off offset:1024
	global_store_short v[76:77], v35, off offset:2048
	global_store_short_d16_hi v[76:77], v35, off offset:3072
	s_mov_b64 s[6:7], 0

; DI float bf2f(u16 v) { return __uint_as_float(((unsigned)v) << 16); }
; template <int NB1>
; DI void hyena_item(const Params& p, char* wsb, int layer, int c, char* lds) {
;     ...
;         for (int g4 = 0; g4 < 4; ++g4) {
;           const int t0 = 8 * g4 + 4 * h, t = 32 * tt1[j] + t0;
;           const int uidx = (tb[j] * NB1 + tt1[j]) * 40 + t0;
;           const uint2 uu = *(const uint2*)(U + uidx);
;           const uint2 zz = *(const uint2*)(zr + t);
;           const float zm1 = t > 0 ? bf2f(zr[t - 1]) : 0.f;
;           const float zp4 = t + 4 < L ? bf2f(zr[t + 4]) : 0.f;
;           const float zv[6] = {zm1, bf2f((u16)(zz.x & 0xffff)), bf2f((u16)(zz.x >> 16)), bf2f((u16)(zz.y & 0xffff)), bf2f((u16)(zz.y >> 16)), zp4};
;           const float uv[4] = {bf2f((u16)(uu.x & 0xffff)), bf2f((u16)(uu.x >> 16)), bf2f((u16)(uu.y & 0xffff)), bf2f((u16)(uu.y >> 16))};
;           float yv[4];
; #pragma unroll
;           for (int e = 0; e < 4; ++e) {
;             const float xv = w0 * zv[e] + w1 * zv[e + 1] + w2 * zv[e + 2] + bb;
;             yv[e] = xv * (acc[j][4 * g4 + e] + bias * uv[e]);
;           }
;           if (order == 0) *(uint2*)(U + uidx) = make_uint2(pack2(yv[0], yv[1]), pack2(yv[2], yv[3]));
;           else {
;             const size_t row = NB1 == 64 ? (size_t)tb[j] * 2048 + t : (size_t)TL + tb[j] * 256 + t;
;             u16* yo = (u16*)(wsb + OFF_Y) + row * 512 + c;
; #pragma unroll
;             for (int e = 0; e < 4; ++e) yo[(size_t)e * 512] = f2bf(yv[e]);
;           }
.LBB0_878:
	v_lshl_add_u64 v[72:73], v[116:117], 1, v[72:73]
	global_load_dwordx2 v[136:137], v[72:73], off offset:16
	global_load_ushort v247, v[72:73], off offset:24
	ds_read_b64 v[138:139], v148 offset:16
	v_mov_b32_e32 v135, 0
	s_and_saveexec_b64 s[6:7], s[50:51]
	s_cbranch_execz .LBB0_880
	global_load_ushort v34, v[70:71], off offset:14
	s_waitcnt vmcnt(0)
	v_lshlrev_b32_e32 v135, 16, v34
.LBB0_880:
	s_or_b64 exec, exec, s[6:7]
	s_waitcnt vmcnt(1)
	v_and_b32_e32 v170, 0xffff0000, v136
	v_mov_b32_e32 v134, v170
	v_lshlrev_b32_e32 v140, 16, v136
	v_pk_mul_f32 v[134:135], v[128:129], v[134:135]
	v_mov_b32_e32 v123, v122
	v_lshlrev_b32_e32 v171, 16, v137
	v_mov_b32_e32 v127, v126
	v_mov_b32_e32 v125, v124
	s_waitcnt lgkmcnt(0)
	v_lshlrev_b32_e32 v172, 16, v138
	v_and_b32_e32 v173, 0xffff0000, v138
	v_and_b32_e32 v136, 0xffff0000, v137
	v_cndmask_b32_e64 v137, 0, 1, s[16:17]
	v_pk_fma_f32 v[38:39], v[126:127], v[172:173], v[38:39]
	v_cmp_ne_u32_e64 s[6:7], 1, v137
	v_mov_b32_e32 v36, v128
	v_mov_b32_e32 v37, v128
	v_mov_b32_e32 v34, v129
	v_mov_b32_e32 v35, v129
	v_mov_b32_e32 v174, v136
	v_lshlrev_b32_e32 v138, 16, v139
	v_and_b32_e32 v139, 0xffff0000, v139
	v_pk_fma_f32 v[40:41], v[126:127], v[138:139], v[40:41]
	s_andn2_b64 vcc, exec, s[16:17]
	s_mov_b64 s[8:9], -1
	s_waitcnt vmcnt(0)
	v_mov_b32_e32 v141, v247
	v_pk_fma_f32 v[134:135], v[128:129], v[140:141], v[134:135] op_sel:[0,0,1] op_sel_hi:[1,0,0]
	s_nop 0
	v_pk_fma_f32 v[134:135], v[122:123], v[170:171], v[134:135]
	v_and_b32_e32 v137, 16, v141
	v_pk_add_f32 v[134:135], v[124:125], v[134:135]
	v_lshlrev_b32_e32 v175, 16, v141
	v_pk_mul_f32 v[38:39], v[38:39], v[134:135]
	v_pk_mov_b32 v[134:135], v[170:171], v[136:137] op_sel:[1,0]
	v_cvt_pk_bf16_f32 v38, v38, v39
	v_pk_mul_f32 v[134:135], v[36:37], v[134:135]
	s_nop 0
	v_pk_fma_f32 v[134:135], v[34:35], v[170:171], v[134:135]
	s_nop 0
	v_pk_fma_f32 v[134:135], v[122:123], v[174:175], v[134:135]
	s_nop 0
	v_pk_add_f32 v[134:135], v[124:125], v[134:135]
	s_nop 0
	v_pk_mul_f32 v[40:41], v[40:41], v[134:135]
	s_nop 0
	v_cvt_pk_bf16_f32 v39, v40, v41
	s_cbranch_vccnz .LBB0_882
	s_mov_b64 s[8:9], 0
	global_store_short v[78:79], v38, off
	global_store_short_d16_hi v[78:79], v38, off offset:1024
	global_store_short v[78:79], v39, off offset:2048
	global_store_short_d16_hi v[78:79], v39, off offset:3072

; DI float bf2f(u16 v) { return __uint_as_float(((unsigned)v) << 16); }
; template <int NB1>
; DI void hyena_item(const Params& p, char* wsb, int layer, int c, char* lds) {
;     ...
;         for (int g4 = 0; g4 < 4; ++g4) {
;           const int t0 = 8 * g4 + 4 * h, t = 32 * tt1[j] + t0;
;           const int uidx = (tb[j] * NB1 + tt1[j]) * 40 + t0;
;           const uint2 uu = *(const uint2*)(U + uidx);
;           const uint2 zz = *(const uint2*)(zr + t);
;           const float zm1 = t > 0 ? bf2f(zr[t - 1]) : 0.f;
;           const float zp4 = t + 4 < L ? bf2f(zr[t + 4]) : 0.f;
;           const float zv[6] = {zm1, bf2f((u16)(zz.x & 0xffff)), bf2f((u16)(zz.x >> 16)), bf2f((u16)(zz.y & 0xffff)), bf2f((u16)(zz.y >> 16)), zp4};
;           const float uv[4] = {bf2f((u16)(uu.x & 0xffff)), bf2f((u16)(uu.x >> 16)), bf2f((u16)(uu.y & 0xffff)), bf2f((u16)(uu.y >> 16))};
;           float yv[4];
; #pragma unroll
;           for (int e = 0; e < 4; ++e) {
;             const float xv = w0 * zv[e] + w1 * zv[e + 1] + w2 * zv[e + 2] + bb;
;             yv[e] = xv * (acc[j][4 * g4 + e] + bias * uv[e]);
;           }
;           if (order == 0) *(uint2*)(U + uidx) = make_uint2(pack2(yv[0], yv[1]), pack2(yv[2], yv[3]));
;           else {
;             const size_t row = NB1 == 64 ? (size_t)tb[j] * 2048 + t : (size_t)TL + tb[j] * 256 + t;
;             u16* yo = (u16*)(wsb + OFF_Y) + row * 512 + c;
; #pragma unroll
;             for (int e = 0; e < 4; ++e) yo[(size_t)e * 512] = f2bf(yv[e]);
;           }
.LBB0_884:
	global_load_dwordx2 v[40:41], v[72:73], off offset:32
	global_load_ushort v248, v[72:73], off offset:40
	ds_read_b64 v[134:135], v148 offset:32
	v_mov_b32_e32 v39, 0
	s_and_saveexec_b64 s[8:9], s[52:53]
	s_cbranch_execz .LBB0_886
	global_load_ushort v38, v[70:71], off offset:30
	s_waitcnt vmcnt(0)
	v_lshlrev_b32_e32 v39, 16, v38
.LBB0_886:
	s_or_b64 exec, exec, s[8:9]
	s_waitcnt vmcnt(1)
	v_lshlrev_b32_e32 v136, 16, v40
	v_and_b32_e32 v138, 0xffff0000, v40
	v_lshlrev_b32_e32 v139, 16, v41
	v_and_b32_e32 v40, 0xffff0000, v41
	v_mov_b32_e32 v170, v40
	v_mov_b32_e32 v38, v138
	v_pk_mul_f32 v[38:39], v[128:129], v[38:39]
	s_waitcnt lgkmcnt(0)
	v_lshlrev_b32_e32 v140, 16, v134
	v_and_b32_e32 v141, 0xffff0000, v134
	v_lshlrev_b32_e32 v134, 16, v135
	v_and_b32_e32 v135, 0xffff0000, v135
	v_pk_fma_f32 v[42:43], v[126:127], v[140:141], v[42:43]
	v_pk_fma_f32 v[44:45], v[126:127], v[134:135], v[44:45]
	s_and_b64 vcc, exec, s[6:7]
	s_mov_b64 s[8:9], -1
	s_waitcnt vmcnt(0)
	v_mov_b32_e32 v137, v248
	v_and_b32_e32 v41, 16, v137
	v_pk_mov_b32 v[40:41], v[138:139], v[40:41] op_sel:[1,0]
	v_pk_fma_f32 v[38:39], v[128:129], v[136:137], v[38:39] op_sel:[0,0,1] op_sel_hi:[1,0,0]
	v_pk_mul_f32 v[40:41], v[36:37], v[40:41]
	v_lshlrev_b32_e32 v171, 16, v137
	v_pk_fma_f32 v[40:41], v[34:35], v[138:139], v[40:41]
	v_pk_fma_f32 v[38:39], v[122:123], v[138:139], v[38:39]
	v_pk_fma_f32 v[40:41], v[122:123], v[170:171], v[40:41]
	v_pk_add_f32 v[38:39], v[124:125], v[38:39]
	v_pk_add_f32 v[40:41], v[124:125], v[40:41]
	v_pk_mul_f32 v[38:39], v[42:43], v[38:39]
	v_pk_mul_f32 v[40:41], v[44:45], v[40:41]
	v_cvt_pk_bf16_f32 v38, v38, v39
	v_cvt_pk_bf16_f32 v39, v40, v41
	s_cbranch_vccnz .LBB0_888
	s_mov_b64 s[8:9], 0
	global_store_short v[80:81], v38, off
	global_store_short_d16_hi v[80:81], v38, off offset:1024
	global_store_short v[80:81], v39, off offset:2048
	global_store_short_d16_hi v[80:81], v39, off offset:3072

; DI float bf2f(u16 v) { return __uint_as_float(((unsigned)v) << 16); }
; template <int NB1>
; DI void hyena_item(const Params& p, char* wsb, int layer, int c, char* lds) {
;     ...
;         for (int g4 = 0; g4 < 4; ++g4) {
;           const int t0 = 8 * g4 + 4 * h, t = 32 * tt1[j] + t0;
;           const int uidx = (tb[j] * NB1 + tt1[j]) * 40 + t0;
;           const uint2 uu = *(const uint2*)(U + uidx);
;           const uint2 zz = *(const uint2*)(zr + t);
;           const float zm1 = t > 0 ? bf2f(zr[t - 1]) : 0.f;
;           const float zp4 = t + 4 < L ? bf2f(zr[t + 4]) : 0.f;
;           const float zv[6] = {zm1, bf2f((u16)(zz.x & 0xffff)), bf2f((u16)(zz.x >> 16)), bf2f((u16)(zz.y & 0xffff)), bf2f((u16)(zz.y >> 16)), zp4};
;           const float uv[4] = {bf2f((u16)(uu.x & 0xffff)), bf2f((u16)(uu.x >> 16)), bf2f((u16)(uu.y & 0xffff)), bf2f((u16)(uu.y >> 16))};
;           float yv[4];
; #pragma unroll
;           for (int e = 0; e < 4; ++e) {
;             const float xv = w0 * zv[e] + w1 * zv[e + 1] + w2 * zv[e + 2] + bb;
;             yv[e] = xv * (acc[j][4 * g4 + e] + bias * uv[e]);
;           }
;           if (order == 0) *(uint2*)(U + uidx) = make_uint2(pack2(yv[0], yv[1]), pack2(yv[2], yv[3]));
;           else {
;             const size_t row = NB1 == 64 ? (size_t)tb[j] * 2048 + t : (size_t)TL + tb[j] * 256 + t;
;             u16* yo = (u16*)(wsb + OFF_Y) + row * 512 + c;
; #pragma unroll
;             for (int e = 0; e < 4; ++e) yo[(size_t)e * 512] = f2bf(yv[e]);
;           }
.LBB0_898:
	v_add_u32_e32 v38, s11, v150
	v_ashrrev_i32_e32 v39, 31, v38
	v_lshlrev_b64 v[38:39], 12, v[38:39]
	v_lshl_add_u64 v[40:41], s[36:37], 0, v[38:39]
	v_lshl_add_u64 v[48:49], v[84:85], 1, v[40:41]
	global_load_dwordx2 v[44:45], v[48:49], off
	global_load_ushort v249, v[48:49], off offset:8
	ds_read_b64 v[46:47], v151
	v_mov_b32_e32 v43, 0
	v_lshl_add_u64 v[38:39], v[86:87], 1, v[40:41]
	s_and_saveexec_b64 s[8:9], s[58:59]
	s_cbranch_execz .LBB0_900
	global_load_ushort v42, v[38:39], off offset:-2
	s_waitcnt vmcnt(0)
	v_lshlrev_b32_e32 v43, 16, v42
.LBB0_900:
	s_or_b64 exec, exec, s[8:9]
	s_waitcnt vmcnt(1)
	v_lshlrev_b32_e32 v48, 16, v44
	v_and_b32_e32 v70, 0xffff0000, v44
	v_lshlrev_b32_e32 v71, 16, v45
	v_and_b32_e32 v44, 0xffff0000, v45
	v_mov_b32_e32 v134, v44
	v_mov_b32_e32 v42, v70
	v_pk_mul_f32 v[42:43], v[128:129], v[42:43]
	s_waitcnt lgkmcnt(0)
	v_lshlrev_b32_e32 v72, 16, v46
	v_and_b32_e32 v73, 0xffff0000, v46
	v_lshlrev_b32_e32 v46, 16, v47
	v_and_b32_e32 v47, 0xffff0000, v47
	v_pk_fma_f32 v[50:51], v[126:127], v[72:73], v[50:51]
	v_pk_fma_f32 v[46:47], v[126:127], v[46:47], v[52:53]
	s_and_b64 vcc, exec, s[6:7]
	s_mov_b64 s[8:9], -1
	s_waitcnt vmcnt(0)
	v_mov_b32_e32 v49, v249
	v_and_b32_e32 v45, 16, v49
	v_pk_mov_b32 v[44:45], v[70:71], v[44:45] op_sel:[1,0]
	v_pk_fma_f32 v[42:43], v[128:129], v[48:49], v[42:43] op_sel:[0,0,1] op_sel_hi:[1,0,0]
	v_pk_mul_f32 v[44:45], v[36:37], v[44:45]
	v_lshlrev_b32_e32 v135, 16, v49
	v_pk_fma_f32 v[44:45], v[34:35], v[70:71], v[44:45]
	v_pk_fma_f32 v[42:43], v[122:123], v[70:71], v[42:43]
	v_pk_fma_f32 v[44:45], v[122:123], v[134:135], v[44:45]
	v_pk_add_f32 v[42:43], v[124:125], v[42:43]
	v_pk_add_f32 v[44:45], v[124:125], v[44:45]
	v_pk_mul_f32 v[42:43], v[50:51], v[42:43]
	v_pk_mul_f32 v[44:45], v[46:47], v[44:45]
	v_cvt_pk_bf16_f32 v42, v42, v43
	v_cvt_pk_bf16_f32 v43, v44, v45
	s_cbranch_vccnz .LBB0_902
	s_mov_b64 s[8:9], 0
	global_store_short v[88:89], v42, off
	global_store_short_d16_hi v[88:89], v42, off offset:1024
	global_store_short v[88:89], v43, off offset:2048
	global_store_short_d16_hi v[88:89], v43, off offset:3072

; DI float bf2f(u16 v) { return __uint_as_float(((unsigned)v) << 16); }
; template <int NB1>
; DI void hyena_item(const Params& p, char* wsb, int layer, int c, char* lds) {
;     ...
;         for (int g4 = 0; g4 < 4; ++g4) {
;           const int t0 = 8 * g4 + 4 * h, t = 32 * tt1[j] + t0;
;           const int uidx = (tb[j] * NB1 + tt1[j]) * 40 + t0;
;           const uint2 uu = *(const uint2*)(U + uidx);
;           const uint2 zz = *(const uint2*)(zr + t);
;           const float zm1 = t > 0 ? bf2f(zr[t - 1]) : 0.f;
;           const float zp4 = t + 4 < L ? bf2f(zr[t + 4]) : 0.f;
;           const float zv[6] = {zm1, bf2f((u16)(zz.x & 0xffff)), bf2f((u16)(zz.x >> 16)), bf2f((u16)(zz.y & 0xffff)), bf2f((u16)(zz.y >> 16)), zp4};
;           const float uv[4] = {bf2f((u16)(uu.x & 0xffff)), bf2f((u16)(uu.x >> 16)), bf2f((u16)(uu.y & 0xffff)), bf2f((u16)(uu.y >> 16))};
;           float yv[4];
; #pragma unroll
;           for (int e = 0; e < 4; ++e) {
;             const float xv = w0 * zv[e] + w1 * zv[e + 1] + w2 * zv[e + 2] + bb;
;             yv[e] = xv * (acc[j][4 * g4 + e] + bias * uv[e]);
;           }
;           if (order == 0) *(uint2*)(U + uidx) = make_uint2(pack2(yv[0], yv[1]), pack2(yv[2], yv[3]));
;           else {
;             const size_t row = NB1 == 64 ? (size_t)tb[j] * 2048 + t : (size_t)TL + tb[j] * 256 + t;
;             u16* yo = (u16*)(wsb + OFF_Y) + row * 512 + c;
; #pragma unroll
;             for (int e = 0; e < 4; ++e) yo[(size_t)e * 512] = f2bf(yv[e]);
;           }
.LBB0_904:
	v_lshl_add_u64 v[40:41], v[118:119], 1, v[40:41]
	global_load_dwordx2 v[44:45], v[40:41], off offset:16
	global_load_ushort v250, v[40:41], off offset:24
	ds_read_b64 v[46:47], v151 offset:16
	v_mov_b32_e32 v43, 0
	s_and_saveexec_b64 s[8:9], s[60:61]
	s_cbranch_execz .LBB0_906
	global_load_ushort v42, v[38:39], off offset:14
	s_waitcnt vmcnt(0)
	v_lshlrev_b32_e32 v43, 16, v42
.LBB0_906:
	s_or_b64 exec, exec, s[8:9]
	s_waitcnt vmcnt(1)
	v_lshlrev_b32_e32 v48, 16, v44
	v_and_b32_e32 v50, 0xffff0000, v44
	v_lshlrev_b32_e32 v51, 16, v45
	v_and_b32_e32 v44, 0xffff0000, v45
	v_mov_b32_e32 v70, v44
	v_mov_b32_e32 v42, v50
	v_pk_mul_f32 v[42:43], v[128:129], v[42:43]
	s_waitcnt lgkmcnt(0)
	v_lshlrev_b32_e32 v52, 16, v46
	v_and_b32_e32 v53, 0xffff0000, v46
	v_lshlrev_b32_e32 v46, 16, v47
	v_and_b32_e32 v47, 0xffff0000, v47
	v_pk_fma_f32 v[52:53], v[126:127], v[52:53], v[54:55]
	v_pk_fma_f32 v[46:47], v[126:127], v[46:47], v[56:57]
	s_and_b64 vcc, exec, s[6:7]
	s_mov_b64 s[8:9], -1
	s_waitcnt vmcnt(0)
	v_mov_b32_e32 v49, v250
	v_and_b32_e32 v45, 16, v49
	v_pk_mov_b32 v[44:45], v[50:51], v[44:45] op_sel:[1,0]
	v_pk_fma_f32 v[42:43], v[128:129], v[48:49], v[42:43] op_sel:[0,0,1] op_sel_hi:[1,0,0]
	v_pk_mul_f32 v[44:45], v[36:37], v[44:45]
	v_lshlrev_b32_e32 v71, 16, v49
	v_pk_fma_f32 v[44:45], v[34:35], v[50:51], v[44:45]
	v_pk_fma_f32 v[42:43], v[122:123], v[50:51], v[42:43]
	v_pk_fma_f32 v[44:45], v[122:123], v[70:71], v[44:45]
	v_pk_add_f32 v[42:43], v[124:125], v[42:43]
	v_pk_add_f32 v[44:45], v[124:125], v[44:45]
	v_pk_mul_f32 v[42:43], v[52:53], v[42:43]
	v_pk_mul_f32 v[44:45], v[46:47], v[44:45]
	v_cvt_pk_bf16_f32 v42, v42, v43
	v_cvt_pk_bf16_f32 v43, v44, v45
	s_cbranch_vccnz .LBB0_908
	s_mov_b64 s[8:9], 0
	global_store_short v[90:91], v42, off
	global_store_short_d16_hi v[90:91], v42, off offset:1024
	global_store_short v[90:91], v43, off offset:2048
	global_store_short_d16_hi v[90:91], v43, off offset:3072

; DI float bf2f(u16 v) { return __uint_as_float(((unsigned)v) << 16); }
; template <int NB1>
; DI void hyena_item(const Params& p, char* wsb, int layer, int c, char* lds) {
;     ...
;         for (int g4 = 0; g4 < 4; ++g4) {
;           const int t0 = 8 * g4 + 4 * h, t = 32 * tt1[j] + t0;
;           const int uidx = (tb[j] * NB1 + tt1[j]) * 40 + t0;
;           const uint2 uu = *(const uint2*)(U + uidx);
;           const uint2 zz = *(const uint2*)(zr + t);
;           const float zm1 = t > 0 ? bf2f(zr[t - 1]) : 0.f;
;           const float zp4 = t + 4 < L ? bf2f(zr[t + 4]) : 0.f;
;           const float zv[6] = {zm1, bf2f((u16)(zz.x & 0xffff)), bf2f((u16)(zz.x >> 16)), bf2f((u16)(zz.y & 0xffff)), bf2f((u16)(zz.y >> 16)), zp4};
;           const float uv[4] = {bf2f((u16)(uu.x & 0xffff)), bf2f((u16)(uu.x >> 16)), bf2f((u16)(uu.y & 0xffff)), bf2f((u16)(uu.y >> 16))};
;           float yv[4];
; #pragma unroll
;           for (int e = 0; e < 4; ++e) {
;             const float xv = w0 * zv[e] + w1 * zv[e + 1] + w2 * zv[e + 2] + bb;
;             yv[e] = xv * (acc[j][4 * g4 + e] + bias * uv[e]);
;           }
;           if (order == 0) *(uint2*)(U + uidx) = make_uint2(pack2(yv[0], yv[1]), pack2(yv[2], yv[3]));
;           else {
;             const size_t row = NB1 == 64 ? (size_t)tb[j] * 2048 + t : (size_t)TL + tb[j] * 256 + t;
;             u16* yo = (u16*)(wsb + OFF_Y) + row * 512 + c;
; #pragma unroll
;             for (int e = 0; e < 4; ++e) yo[(size_t)e * 512] = f2bf(yv[e]);
;           }
.LBB0_910:
	global_load_dwordx2 v[44:45], v[40:41], off offset:32
	global_load_ushort v251, v[40:41], off offset:40
	ds_read_b64 v[46:47], v151 offset:32
	v_mov_b32_e32 v43, 0
	s_and_saveexec_b64 s[8:9], s[62:63]
	s_cbranch_execz .LBB0_912
	global_load_ushort v42, v[38:39], off offset:30
	s_waitcnt vmcnt(0)
	v_lshlrev_b32_e32 v43, 16, v42
.LBB0_912:
	s_or_b64 exec, exec, s[8:9]
	s_waitcnt vmcnt(1)
	v_lshlrev_b32_e32 v48, 16, v44
	v_and_b32_e32 v50, 0xffff0000, v44
	v_lshlrev_b32_e32 v51, 16, v45
	v_and_b32_e32 v44, 0xffff0000, v45
	v_mov_b32_e32 v54, v44
	v_mov_b32_e32 v42, v50
	v_pk_mul_f32 v[42:43], v[128:129], v[42:43]
	s_waitcnt lgkmcnt(0)
	v_lshlrev_b32_e32 v52, 16, v46
	v_and_b32_e32 v53, 0xffff0000, v46
	v_lshlrev_b32_e32 v46, 16, v47
	v_and_b32_e32 v47, 0xffff0000, v47
	v_pk_fma_f32 v[52:53], v[126:127], v[52:53], v[58:59]
	v_pk_fma_f32 v[46:47], v[126:127], v[46:47], v[60:61]
	s_and_b64 vcc, exec, s[6:7]
	s_mov_b64 s[8:9], -1
	s_waitcnt vmcnt(0)
	v_mov_b32_e32 v49, v251
	v_and_b32_e32 v45, 16, v49
	v_pk_mov_b32 v[44:45], v[50:51], v[44:45] op_sel:[1,0]
	v_pk_fma_f32 v[42:43], v[128:129], v[48:49], v[42:43] op_sel:[0,0,1] op_sel_hi:[1,0,0]
	v_pk_mul_f32 v[44:45], v[36:37], v[44:45]
	v_lshlrev_b32_e32 v55, 16, v49
	v_pk_fma_f32 v[44:45], v[34:35], v[50:51], v[44:45]
	v_pk_fma_f32 v[42:43], v[122:123], v[50:51], v[42:43]
	v_pk_fma_f32 v[44:45], v[122:123], v[54:55], v[44:45]
	v_pk_add_f32 v[42:43], v[124:125], v[42:43]
	v_pk_add_f32 v[44:45], v[124:125], v[44:45]
	v_pk_mul_f32 v[42:43], v[52:53], v[42:43]
	v_pk_mul_f32 v[44:45], v[46:47], v[44:45]
	v_cvt_pk_bf16_f32 v42, v42, v43
	v_cvt_pk_bf16_f32 v43, v44, v45
	s_cbranch_vccnz .LBB0_914
	s_mov_b64 s[8:9], 0
	global_store_short v[92:93], v42, off
	global_store_short_d16_hi v[92:93], v42, off offset:1024
	global_store_short v[92:93], v43, off offset:2048
	global_store_short_d16_hi v[92:93], v43, off offset:3072

; DI float bf2f(u16 v) { return __uint_as_float(((unsigned)v) << 16); }
; template <int NB1>
; DI void hyena_item(const Params& p, char* wsb, int layer, int c, char* lds) {
;     ...
;         for (int g4 = 0; g4 < 4; ++g4) {
;           const int t0 = 8 * g4 + 4 * h, t = 32 * tt1[j] + t0;
;           const int uidx = (tb[j] * NB1 + tt1[j]) * 40 + t0;
;           const uint2 uu = *(const uint2*)(U + uidx);
;           const uint2 zz = *(const uint2*)(zr + t);
;           const float zm1 = t > 0 ? bf2f(zr[t - 1]) : 0.f;
;           const float zp4 = t + 4 < L ? bf2f(zr[t + 4]) : 0.f;
;           const float zv[6] = {zm1, bf2f((u16)(zz.x & 0xffff)), bf2f((u16)(zz.x >> 16)), bf2f((u16)(zz.y & 0xffff)), bf2f((u16)(zz.y >> 16)), zp4};
;           const float uv[4] = {bf2f((u16)(uu.x & 0xffff)), bf2f((u16)(uu.x >> 16)), bf2f((u16)(uu.y & 0xffff)), bf2f((u16)(uu.y >> 16))};
;           float yv[4];
; #pragma unroll
;           for (int e = 0; e < 4; ++e) {
;             const float xv = w0 * zv[e] + w1 * zv[e + 1] + w2 * zv[e + 2] + bb;
;             yv[e] = xv * (acc[j][4 * g4 + e] + bias * uv[e]);
;           }
;           if (order == 0) *(uint2*)(U + uidx) = make_uint2(pack2(yv[0], yv[1]), pack2(yv[2], yv[3]));
;           else {
;             const size_t row = NB1 == 64 ? (size_t)tb[j] * 2048 + t : (size_t)TL + tb[j] * 256 + t;
;             u16* yo = (u16*)(wsb + OFF_Y) + row * 512 + c;
; #pragma unroll
;             for (int e = 0; e < 4; ++e) yo[(size_t)e * 512] = f2bf(yv[e]);
;           }
.LBB0_924:
	v_add_u32_e32 v38, s11, v152
	v_ashrrev_i32_e32 v39, 31, v38
	v_lshlrev_b64 v[38:39], 12, v[38:39]
	v_lshl_add_u64 v[40:41], s[36:37], 0, v[38:39]
	v_lshl_add_u64 v[48:49], v[74:75], 1, v[40:41]
	global_load_dwordx2 v[44:45], v[48:49], off
	global_load_ushort v252, v[48:49], off offset:8
	ds_read_b64 v[46:47], v153
	v_mov_b32_e32 v43, 0
	v_lshl_add_u64 v[38:39], v[0:1], 1, v[40:41]
	s_and_saveexec_b64 s[8:9], s[48:49]
	s_cbranch_execz .LBB0_926
	global_load_ushort v42, v[38:39], off offset:-2
	s_waitcnt vmcnt(0)
	v_lshlrev_b32_e32 v43, 16, v42
.LBB0_926:
	s_or_b64 exec, exec, s[8:9]
	s_waitcnt vmcnt(1)
	v_and_b32_e32 v50, 0xffff0000, v44
	v_mov_b32_e32 v42, v50
	v_lshlrev_b32_e32 v48, 16, v44
	v_pk_mul_f32 v[42:43], v[128:129], v[42:43]
	v_lshlrev_b32_e32 v51, 16, v45
	s_waitcnt lgkmcnt(0)
	v_lshlrev_b32_e32 v52, 16, v46
	v_and_b32_e32 v53, 0xffff0000, v46
	v_and_b32_e32 v44, 0xffff0000, v45
	v_pk_fma_f32 v[2:3], v[126:127], v[52:53], v[2:3]
	v_mov_b32_e32 v54, v44
	v_lshlrev_b32_e32 v46, 16, v47
	v_and_b32_e32 v47, 0xffff0000, v47
	v_pk_fma_f32 v[4:5], v[126:127], v[46:47], v[4:5]
	s_and_b64 vcc, exec, s[6:7]
	s_mov_b64 s[8:9], -1
	s_waitcnt vmcnt(0)
	v_mov_b32_e32 v49, v252
	v_pk_fma_f32 v[42:43], v[128:129], v[48:49], v[42:43] op_sel:[0,0,1] op_sel_hi:[1,0,0]
	s_nop 0
	v_pk_fma_f32 v[42:43], v[122:123], v[50:51], v[42:43]
	v_and_b32_e32 v45, 16, v49
	v_pk_add_f32 v[42:43], v[124:125], v[42:43]
	v_lshlrev_b32_e32 v55, 16, v49
	v_pk_mul_f32 v[2:3], v[2:3], v[42:43]
	v_pk_mov_b32 v[42:43], v[50:51], v[44:45] op_sel:[1,0]
	v_cvt_pk_bf16_f32 v2, v2, v3
	v_pk_mul_f32 v[42:43], v[36:37], v[42:43]
	s_nop 0
	v_pk_fma_f32 v[42:43], v[34:35], v[50:51], v[42:43]
	s_nop 0
	v_pk_fma_f32 v[42:43], v[122:123], v[54:55], v[42:43]
	s_nop 0
	v_pk_add_f32 v[42:43], v[124:125], v[42:43]
	s_nop 0
	v_pk_mul_f32 v[4:5], v[4:5], v[42:43]
	s_nop 0
	v_cvt_pk_bf16_f32 v3, v4, v5
	s_cbranch_vccnz .LBB0_928
	s_mov_b64 s[8:9], 0
	global_store_short v[96:97], v2, off
	global_store_short_d16_hi v[96:97], v2, off offset:1024
	global_store_short v[96:97], v3, off offset:2048
	global_store_short_d16_hi v[96:97], v3, off offset:3072

; DI float bf2f(u16 v) { return __uint_as_float(((unsigned)v) << 16); }
; template <int NB1>
; DI void hyena_item(const Params& p, char* wsb, int layer, int c, char* lds) {
;     ...
;         for (int g4 = 0; g4 < 4; ++g4) {
;           const int t0 = 8 * g4 + 4 * h, t = 32 * tt1[j] + t0;
;           const int uidx = (tb[j] * NB1 + tt1[j]) * 40 + t0;
;           const uint2 uu = *(const uint2*)(U + uidx);
;           const uint2 zz = *(const uint2*)(zr + t);
;           const float zm1 = t > 0 ? bf2f(zr[t - 1]) : 0.f;
;           const float zp4 = t + 4 < L ? bf2f(zr[t + 4]) : 0.f;
;           const float zv[6] = {zm1, bf2f((u16)(zz.x & 0xffff)), bf2f((u16)(zz.x >> 16)), bf2f((u16)(zz.y & 0xffff)), bf2f((u16)(zz.y >> 16)), zp4};
;           const float uv[4] = {bf2f((u16)(uu.x & 0xffff)), bf2f((u16)(uu.x >> 16)), bf2f((u16)(uu.y & 0xffff)), bf2f((u16)(uu.y >> 16))};
;           float yv[4];
; #pragma unroll
;           for (int e = 0; e < 4; ++e) {
;             const float xv = w0 * zv[e] + w1 * zv[e + 1] + w2 * zv[e + 2] + bb;
;             yv[e] = xv * (acc[j][4 * g4 + e] + bias * uv[e]);
;           }
;           if (order == 0) *(uint2*)(U + uidx) = make_uint2(pack2(yv[0], yv[1]), pack2(yv[2], yv[3]));
;           else {
;             const size_t row = NB1 == 64 ? (size_t)tb[j] * 2048 + t : (size_t)TL + tb[j] * 256 + t;
;             u16* yo = (u16*)(wsb + OFF_Y) + row * 512 + c;
; #pragma unroll
;             for (int e = 0; e < 4; ++e) yo[(size_t)e * 512] = f2bf(yv[e]);
;           }
.LBB0_930:
	v_lshl_add_u64 v[2:3], v[116:117], 1, v[40:41]
	global_load_dwordx2 v[40:41], v[2:3], off offset:16
	global_load_ushort v253, v[2:3], off offset:24
	ds_read_b64 v[42:43], v153 offset:16
	v_mov_b32_e32 v5, 0
	s_and_saveexec_b64 s[8:9], s[50:51]
	s_cbranch_execz .LBB0_932
	global_load_ushort v4, v[38:39], off offset:14
	s_waitcnt vmcnt(0)
	v_lshlrev_b32_e32 v5, 16, v4
.LBB0_932:
	s_or_b64 exec, exec, s[8:9]
	s_waitcnt vmcnt(1)
	v_and_b32_e32 v46, 0xffff0000, v40
	v_mov_b32_e32 v4, v46
	v_lshlrev_b32_e32 v44, 16, v40
	v_pk_mul_f32 v[4:5], v[128:129], v[4:5]
	v_lshlrev_b32_e32 v47, 16, v41
	s_waitcnt lgkmcnt(0)
	v_lshlrev_b32_e32 v48, 16, v42
	v_and_b32_e32 v49, 0xffff0000, v42
	v_and_b32_e32 v40, 0xffff0000, v41
	v_pk_fma_f32 v[6:7], v[126:127], v[48:49], v[6:7]
	v_mov_b32_e32 v50, v40
	v_lshlrev_b32_e32 v42, 16, v43
	v_and_b32_e32 v43, 0xffff0000, v43
	v_pk_fma_f32 v[8:9], v[126:127], v[42:43], v[8:9]
	s_and_b64 vcc, exec, s[6:7]
	s_mov_b64 s[8:9], -1
	s_waitcnt vmcnt(0)
	v_mov_b32_e32 v45, v253
	v_pk_fma_f32 v[4:5], v[128:129], v[44:45], v[4:5] op_sel:[0,0,1] op_sel_hi:[1,0,0]
	s_nop 0
	v_pk_fma_f32 v[4:5], v[122:123], v[46:47], v[4:5]
	v_and_b32_e32 v41, 16, v45
	v_pk_add_f32 v[4:5], v[124:125], v[4:5]
	v_lshlrev_b32_e32 v51, 16, v45
	v_pk_mul_f32 v[4:5], v[6:7], v[4:5]
	v_pk_mov_b32 v[6:7], v[46:47], v[40:41] op_sel:[1,0]
	v_cvt_pk_bf16_f32 v4, v4, v5
	v_pk_mul_f32 v[6:7], v[36:37], v[6:7]
	s_nop 0
	v_pk_fma_f32 v[6:7], v[34:35], v[46:47], v[6:7]
	s_nop 0
	v_pk_fma_f32 v[6:7], v[122:123], v[50:51], v[6:7]
	s_nop 0
	v_pk_add_f32 v[6:7], v[124:125], v[6:7]
	s_nop 0
	v_pk_mul_f32 v[6:7], v[8:9], v[6:7]
	s_nop 0
	v_cvt_pk_bf16_f32 v5, v6, v7
	s_cbranch_vccnz .LBB0_934
	s_mov_b64 s[8:9], 0
	global_store_short v[98:99], v4, off
	global_store_short_d16_hi v[98:99], v4, off offset:1024
	global_store_short v[98:99], v5, off offset:2048
	global_store_short_d16_hi v[98:99], v5, off offset:3072

; DI float bf2f(u16 v) { return __uint_as_float(((unsigned)v) << 16); }
; template <int NB1>
; DI void hyena_item(const Params& p, char* wsb, int layer, int c, char* lds) {
;     ...
;         for (int g4 = 0; g4 < 4; ++g4) {
;           const int t0 = 8 * g4 + 4 * h, t = 32 * tt1[j] + t0;
;           const int uidx = (tb[j] * NB1 + tt1[j]) * 40 + t0;
;           const uint2 uu = *(const uint2*)(U + uidx);
;           const uint2 zz = *(const uint2*)(zr + t);
;           const float zm1 = t > 0 ? bf2f(zr[t - 1]) : 0.f;
;           const float zp4 = t + 4 < L ? bf2f(zr[t + 4]) : 0.f;
;           const float zv[6] = {zm1, bf2f((u16)(zz.x & 0xffff)), bf2f((u16)(zz.x >> 16)), bf2f((u16)(zz.y & 0xffff)), bf2f((u16)(zz.y >> 16)), zp4};
;           const float uv[4] = {bf2f((u16)(uu.x & 0xffff)), bf2f((u16)(uu.x >> 16)), bf2f((u16)(uu.y & 0xffff)), bf2f((u16)(uu.y >> 16))};
;           float yv[4];
; #pragma unroll
;           for (int e = 0; e < 4; ++e) {
;             const float xv = w0 * zv[e] + w1 * zv[e + 1] + w2 * zv[e + 2] + bb;
;             yv[e] = xv * (acc[j][4 * g4 + e] + bias * uv[e]);
;           }
;           if (order == 0) *(uint2*)(U + uidx) = make_uint2(pack2(yv[0], yv[1]), pack2(yv[2], yv[3]));
;           else {
;             const size_t row = NB1 == 64 ? (size_t)tb[j] * 2048 + t : (size_t)TL + tb[j] * 256 + t;
;             u16* yo = (u16*)(wsb + OFF_Y) + row * 512 + c;
; #pragma unroll
;             for (int e = 0; e < 4; ++e) yo[(size_t)e * 512] = f2bf(yv[e]);
;           }
.LBB0_936:
	global_load_dwordx2 v[6:7], v[2:3], off offset:32
	global_load_ushort v246, v[2:3], off offset:40
	ds_read_b64 v[8:9], v153 offset:32
	v_mov_b32_e32 v5, 0
	s_and_saveexec_b64 s[8:9], s[52:53]
	s_cbranch_execz .LBB0_938
	global_load_ushort v4, v[38:39], off offset:30
	s_waitcnt vmcnt(0)
	v_lshlrev_b32_e32 v5, 16, v4
.LBB0_938:
	s_or_b64 exec, exec, s[8:9]
	s_waitcnt vmcnt(1)
	v_lshlrev_b32_e32 v40, 16, v6
	v_and_b32_e32 v42, 0xffff0000, v6
	v_lshlrev_b32_e32 v43, 16, v7
	v_and_b32_e32 v6, 0xffff0000, v7
	v_mov_b32_e32 v46, v6
	v_mov_b32_e32 v4, v42
	v_pk_mul_f32 v[4:5], v[128:129], v[4:5]
	s_waitcnt lgkmcnt(0)
	v_lshlrev_b32_e32 v44, 16, v8
	v_and_b32_e32 v45, 0xffff0000, v8
	v_lshlrev_b32_e32 v8, 16, v9
	v_and_b32_e32 v9, 0xffff0000, v9
	v_pk_fma_f32 v[10:11], v[126:127], v[44:45], v[10:11]
	v_pk_fma_f32 v[8:9], v[126:127], v[8:9], v[12:13]
	s_and_b64 vcc, exec, s[6:7]
	s_mov_b64 s[8:9], -1
	s_waitcnt vmcnt(0)
	v_mov_b32_e32 v41, v246
	v_and_b32_e32 v7, 16, v41
	v_pk_mov_b32 v[6:7], v[42:43], v[6:7] op_sel:[1,0]
	v_pk_fma_f32 v[4:5], v[128:129], v[40:41], v[4:5] op_sel:[0,0,1] op_sel_hi:[1,0,0]
	v_pk_mul_f32 v[6:7], v[36:37], v[6:7]
	v_lshlrev_b32_e32 v47, 16, v41
	v_pk_fma_f32 v[6:7], v[34:35], v[42:43], v[6:7]
	v_pk_fma_f32 v[4:5], v[122:123], v[42:43], v[4:5]
	v_pk_fma_f32 v[6:7], v[122:123], v[46:47], v[6:7]
	v_pk_add_f32 v[4:5], v[124:125], v[4:5]
	v_pk_add_f32 v[6:7], v[124:125], v[6:7]
	v_pk_mul_f32 v[4:5], v[10:11], v[4:5]
	v_pk_mul_f32 v[6:7], v[8:9], v[6:7]
	v_cvt_pk_bf16_f32 v4, v4, v5
	v_cvt_pk_bf16_f32 v5, v6, v7
	s_cbranch_vccnz .LBB0_940
	s_mov_b64 s[8:9], 0
	global_store_short v[100:101], v4, off
	global_store_short_d16_hi v[100:101], v4, off offset:1024
	global_store_short v[100:101], v5, off offset:2048
	global_store_short_d16_hi v[100:101], v5, off offset:3072

; DI float bf2f(u16 v) { return __uint_as_float(((unsigned)v) << 16); }
; template <int NB1>
; DI void hyena_item(const Params& p, char* wsb, int layer, int c, char* lds) {
;     ...
;         for (int g4 = 0; g4 < 4; ++g4) {
;           const int t0 = 8 * g4 + 4 * h, t = 32 * tt1[j] + t0;
;           const int uidx = (tb[j] * NB1 + tt1[j]) * 40 + t0;
;           const uint2 uu = *(const uint2*)(U + uidx);
;           const uint2 zz = *(const uint2*)(zr + t);
;           const float zm1 = t > 0 ? bf2f(zr[t - 1]) : 0.f;
;           const float zp4 = t + 4 < L ? bf2f(zr[t + 4]) : 0.f;
;           const float zv[6] = {zm1, bf2f((u16)(zz.x & 0xffff)), bf2f((u16)(zz.x >> 16)), bf2f((u16)(zz.y & 0xffff)), bf2f((u16)(zz.y >> 16)), zp4};
;           const float uv[4] = {bf2f((u16)(uu.x & 0xffff)), bf2f((u16)(uu.x >> 16)), bf2f((u16)(uu.y & 0xffff)), bf2f((u16)(uu.y >> 16))};
;           float yv[4];
; #pragma unroll
;           for (int e = 0; e < 4; ++e) {
;             const float xv = w0 * zv[e] + w1 * zv[e + 1] + w2 * zv[e + 2] + bb;
;             yv[e] = xv * (acc[j][4 * g4 + e] + bias * uv[e]);
;           }
;           if (order == 0) *(uint2*)(U + uidx) = make_uint2(pack2(yv[0], yv[1]), pack2(yv[2], yv[3]));
;           else {
;             const size_t row = NB1 == 64 ? (size_t)tb[j] * 2048 + t : (size_t)TL + tb[j] * 256 + t;
;             u16* yo = (u16*)(wsb + OFF_Y) + row * 512 + c;
; #pragma unroll
;             for (int e = 0; e < 4; ++e) yo[(size_t)e * 512] = f2bf(yv[e]);
;           }
.LBB0_950:
	v_add_u32_e32 v2, s11, v154
	v_ashrrev_i32_e32 v3, 31, v2
	v_lshlrev_b64 v[2:3], 12, v[2:3]
	v_lshl_add_u64 v[4:5], s[36:37], 0, v[2:3]
	v_lshl_add_u64 v[12:13], v[104:105], 1, v[4:5]
	global_load_dwordx2 v[8:9], v[12:13], off
	global_load_ushort v247, v[12:13], off offset:8
	ds_read_b64 v[10:11], v155
	v_mov_b32_e32 v7, 0
	v_lshl_add_u64 v[2:3], v[106:107], 1, v[4:5]
	s_and_saveexec_b64 s[8:9], s[68:69]
	s_cbranch_execz .LBB0_952
	global_load_ushort v6, v[2:3], off offset:-2
	s_waitcnt vmcnt(0)
	v_lshlrev_b32_e32 v7, 16, v6
.LBB0_952:
	s_or_b64 exec, exec, s[8:9]
	s_waitcnt vmcnt(1)
	v_lshlrev_b32_e32 v12, 16, v8
	v_and_b32_e32 v14, 0xffff0000, v8
	v_lshlrev_b32_e32 v15, 16, v9
	v_and_b32_e32 v8, 0xffff0000, v9
	v_mov_b32_e32 v38, v8
	v_mov_b32_e32 v6, v14
	v_pk_mul_f32 v[6:7], v[128:129], v[6:7]
	s_waitcnt lgkmcnt(0)
	v_lshlrev_b32_e32 v16, 16, v10
	v_and_b32_e32 v17, 0xffff0000, v10
	v_lshlrev_b32_e32 v10, 16, v11
	v_and_b32_e32 v11, 0xffff0000, v11
	v_pk_fma_f32 v[16:17], v[126:127], v[16:17], v[18:19]
	v_pk_fma_f32 v[10:11], v[126:127], v[10:11], v[20:21]
	s_and_b64 vcc, exec, s[6:7]
	s_mov_b64 s[8:9], -1
	s_waitcnt vmcnt(0)
	v_mov_b32_e32 v13, v247
	v_and_b32_e32 v9, 16, v13
	v_pk_mov_b32 v[8:9], v[14:15], v[8:9] op_sel:[1,0]
	v_pk_fma_f32 v[6:7], v[128:129], v[12:13], v[6:7] op_sel:[0,0,1] op_sel_hi:[1,0,0]
	v_pk_mul_f32 v[8:9], v[36:37], v[8:9]
	v_lshlrev_b32_e32 v39, 16, v13
	v_pk_fma_f32 v[8:9], v[34:35], v[14:15], v[8:9]
	v_pk_fma_f32 v[6:7], v[122:123], v[14:15], v[6:7]
	v_pk_fma_f32 v[8:9], v[122:123], v[38:39], v[8:9]
	v_pk_add_f32 v[6:7], v[124:125], v[6:7]
	v_pk_add_f32 v[8:9], v[124:125], v[8:9]
	v_pk_mul_f32 v[6:7], v[16:17], v[6:7]
	v_pk_mul_f32 v[8:9], v[10:11], v[8:9]
	v_cvt_pk_bf16_f32 v6, v6, v7
	v_cvt_pk_bf16_f32 v7, v8, v9
	s_cbranch_vccnz .LBB0_954
	s_mov_b64 s[8:9], 0
	global_store_short v[108:109], v6, off
	global_store_short_d16_hi v[108:109], v6, off offset:1024
	global_store_short v[108:109], v7, off offset:2048
	global_store_short_d16_hi v[108:109], v7, off offset:3072

; DI float bf2f(u16 v) { return __uint_as_float(((unsigned)v) << 16); }
; template <int NB1>
; DI void hyena_item(const Params& p, char* wsb, int layer, int c, char* lds) {
;     ...
;         for (int g4 = 0; g4 < 4; ++g4) {
;           const int t0 = 8 * g4 + 4 * h, t = 32 * tt1[j] + t0;
;           const int uidx = (tb[j] * NB1 + tt1[j]) * 40 + t0;
;           const uint2 uu = *(const uint2*)(U + uidx);
;           const uint2 zz = *(const uint2*)(zr + t);
;           const float zm1 = t > 0 ? bf2f(zr[t - 1]) : 0.f;
;           const float zp4 = t + 4 < L ? bf2f(zr[t + 4]) : 0.f;
;           const float zv[6] = {zm1, bf2f((u16)(zz.x & 0xffff)), bf2f((u16)(zz.x >> 16)), bf2f((u16)(zz.y & 0xffff)), bf2f((u16)(zz.y >> 16)), zp4};
;           const float uv[4] = {bf2f((u16)(uu.x & 0xffff)), bf2f((u16)(uu.x >> 16)), bf2f((u16)(uu.y & 0xffff)), bf2f((u16)(uu.y >> 16))};
;           float yv[4];
; #pragma unroll
;           for (int e = 0; e < 4; ++e) {
;             const float xv = w0 * zv[e] + w1 * zv[e + 1] + w2 * zv[e + 2] + bb;
;             yv[e] = xv * (acc[j][4 * g4 + e] + bias * uv[e]);
;           }
;           if (order == 0) *(uint2*)(U + uidx) = make_uint2(pack2(yv[0], yv[1]), pack2(yv[2], yv[3]));
;           else {
;             const size_t row = NB1 == 64 ? (size_t)tb[j] * 2048 + t : (size_t)TL + tb[j] * 256 + t;
;             u16* yo = (u16*)(wsb + OFF_Y) + row * 512 + c;
; #pragma unroll
;             for (int e = 0; e < 4; ++e) yo[(size_t)e * 512] = f2bf(yv[e]);
;           }
.LBB0_956:
	v_lshl_add_u64 v[4:5], v[120:121], 1, v[4:5]
	global_load_dwordx2 v[8:9], v[4:5], off offset:16
	global_load_ushort v248, v[4:5], off offset:24
	ds_read_b64 v[10:11], v155 offset:16
	v_mov_b32_e32 v7, 0
	s_and_saveexec_b64 s[8:9], s[70:71]
	s_cbranch_execz .LBB0_958
	global_load_ushort v6, v[2:3], off offset:14
	s_waitcnt vmcnt(0)
	v_lshlrev_b32_e32 v7, 16, v6
.LBB0_958:
	s_or_b64 exec, exec, s[8:9]
	s_waitcnt vmcnt(1)
	v_lshlrev_b32_e32 v12, 16, v8
	v_and_b32_e32 v14, 0xffff0000, v8
	v_lshlrev_b32_e32 v15, 16, v9
	v_and_b32_e32 v8, 0xffff0000, v9
	v_mov_b32_e32 v18, v8
	v_mov_b32_e32 v6, v14
	v_pk_mul_f32 v[6:7], v[128:129], v[6:7]
	s_waitcnt lgkmcnt(0)
	v_lshlrev_b32_e32 v16, 16, v10
	v_and_b32_e32 v17, 0xffff0000, v10
	v_lshlrev_b32_e32 v10, 16, v11
	v_and_b32_e32 v11, 0xffff0000, v11
	v_pk_fma_f32 v[16:17], v[126:127], v[16:17], v[22:23]
	v_pk_fma_f32 v[10:11], v[126:127], v[10:11], v[24:25]
	s_and_b64 vcc, exec, s[6:7]
	s_mov_b64 s[8:9], -1
	s_waitcnt vmcnt(0)
	v_mov_b32_e32 v13, v248
	v_and_b32_e32 v9, 16, v13
	v_pk_mov_b32 v[8:9], v[14:15], v[8:9] op_sel:[1,0]
	v_pk_fma_f32 v[6:7], v[128:129], v[12:13], v[6:7] op_sel:[0,0,1] op_sel_hi:[1,0,0]
	v_pk_mul_f32 v[8:9], v[36:37], v[8:9]
	v_lshlrev_b32_e32 v19, 16, v13
	v_pk_fma_f32 v[8:9], v[34:35], v[14:15], v[8:9]
	v_pk_fma_f32 v[6:7], v[122:123], v[14:15], v[6:7]
	v_pk_fma_f32 v[8:9], v[122:123], v[18:19], v[8:9]
	v_pk_add_f32 v[6:7], v[124:125], v[6:7]
	v_pk_add_f32 v[8:9], v[124:125], v[8:9]
	v_pk_mul_f32 v[6:7], v[16:17], v[6:7]
	v_pk_mul_f32 v[8:9], v[10:11], v[8:9]
	v_cvt_pk_bf16_f32 v6, v6, v7
	v_cvt_pk_bf16_f32 v7, v8, v9
	s_cbranch_vccnz .LBB0_960
	s_mov_b64 s[8:9], 0
	global_store_short v[110:111], v6, off
	global_store_short_d16_hi v[110:111], v6, off offset:1024
	global_store_short v[110:111], v7, off offset:2048
	global_store_short_d16_hi v[110:111], v7, off offset:3072

; DI float bf2f(u16 v) { return __uint_as_float(((unsigned)v) << 16); }
; template <int NB1>
; DI void hyena_item(const Params& p, char* wsb, int layer, int c, char* lds) {
;     ...
;         for (int g4 = 0; g4 < 4; ++g4) {
;           const int t0 = 8 * g4 + 4 * h, t = 32 * tt1[j] + t0;
;           const int uidx = (tb[j] * NB1 + tt1[j]) * 40 + t0;
;           const uint2 uu = *(const uint2*)(U + uidx);
;           const uint2 zz = *(const uint2*)(zr + t);
;           const float zm1 = t > 0 ? bf2f(zr[t - 1]) : 0.f;
;           const float zp4 = t + 4 < L ? bf2f(zr[t + 4]) : 0.f;
;           const float zv[6] = {zm1, bf2f((u16)(zz.x & 0xffff)), bf2f((u16)(zz.x >> 16)), bf2f((u16)(zz.y & 0xffff)), bf2f((u16)(zz.y >> 16)), zp4};
;           const float uv[4] = {bf2f((u16)(uu.x & 0xffff)), bf2f((u16)(uu.x >> 16)), bf2f((u16)(uu.y & 0xffff)), bf2f((u16)(uu.y >> 16))};
;           float yv[4];
; #pragma unroll
;           for (int e = 0; e < 4; ++e) {
;             const float xv = w0 * zv[e] + w1 * zv[e + 1] + w2 * zv[e + 2] + bb;
;             yv[e] = xv * (acc[j][4 * g4 + e] + bias * uv[e]);
;           }
;           if (order == 0) *(uint2*)(U + uidx) = make_uint2(pack2(yv[0], yv[1]), pack2(yv[2], yv[3]));
;           else {
;             const size_t row = NB1 == 64 ? (size_t)tb[j] * 2048 + t : (size_t)TL + tb[j] * 256 + t;
;             u16* yo = (u16*)(wsb + OFF_Y) + row * 512 + c;
; #pragma unroll
;             for (int e = 0; e < 4; ++e) yo[(size_t)e * 512] = f2bf(yv[e]);
;           }
.LBB0_962:
	global_load_dwordx2 v[8:9], v[4:5], off offset:32
	global_load_ushort v249, v[4:5], off offset:40
	ds_read_b64 v[10:11], v155 offset:32
	v_mov_b32_e32 v7, 0
	s_and_saveexec_b64 s[8:9], s[72:73]
	s_cbranch_execz .LBB0_964
	global_load_ushort v6, v[2:3], off offset:30
	s_waitcnt vmcnt(0)
	v_lshlrev_b32_e32 v7, 16, v6
.LBB0_964:
	s_or_b64 exec, exec, s[8:9]
	s_waitcnt vmcnt(1)
	v_lshlrev_b32_e32 v12, 16, v8
	v_and_b32_e32 v14, 0xffff0000, v8
	v_lshlrev_b32_e32 v15, 16, v9
	v_and_b32_e32 v8, 0xffff0000, v9
	v_mov_b32_e32 v18, v8
	v_mov_b32_e32 v6, v14
	v_pk_mul_f32 v[6:7], v[128:129], v[6:7]
	s_waitcnt lgkmcnt(0)
	v_lshlrev_b32_e32 v16, 16, v10
	v_and_b32_e32 v17, 0xffff0000, v10
	v_lshlrev_b32_e32 v10, 16, v11
	v_and_b32_e32 v11, 0xffff0000, v11
	v_pk_fma_f32 v[16:17], v[126:127], v[16:17], v[26:27]
	v_pk_fma_f32 v[10:11], v[126:127], v[10:11], v[28:29]
	s_and_b64 vcc, exec, s[6:7]
	s_mov_b64 s[8:9], -1
	s_waitcnt vmcnt(0)
	v_mov_b32_e32 v13, v249
	v_and_b32_e32 v9, 16, v13
	v_pk_mov_b32 v[8:9], v[14:15], v[8:9] op_sel:[1,0]
	v_pk_fma_f32 v[6:7], v[128:129], v[12:13], v[6:7] op_sel:[0,0,1] op_sel_hi:[1,0,0]
	v_pk_mul_f32 v[8:9], v[36:37], v[8:9]
	v_lshlrev_b32_e32 v19, 16, v13
	v_pk_fma_f32 v[8:9], v[34:35], v[14:15], v[8:9]
	v_pk_fma_f32 v[6:7], v[122:123], v[14:15], v[6:7]
	v_pk_fma_f32 v[8:9], v[122:123], v[18:19], v[8:9]
	v_pk_add_f32 v[6:7], v[124:125], v[6:7]
	v_pk_add_f32 v[8:9], v[124:125], v[8:9]
	v_pk_mul_f32 v[6:7], v[16:17], v[6:7]
	v_pk_mul_f32 v[8:9], v[10:11], v[8:9]
	v_cvt_pk_bf16_f32 v6, v6, v7
	v_cvt_pk_bf16_f32 v7, v8, v9
	s_cbranch_vccnz .LBB0_966
	s_mov_b64 s[8:9], 0
	global_store_short v[112:113], v6, off
	global_store_short_d16_hi v[112:113], v6, off offset:1024
	global_store_short v[112:113], v7, off offset:2048
	global_store_short_d16_hi v[112:113], v7, off offset:3072
